# weight-conversion phase: non-temporal (nt) loads for the f32 weights that are read once per launch
# speedup vs baseline: 1.0068x; 1.0068x over previous
; #define LAS __attribute__((address_space(3)))
; #define in KArgIn()
; __device__ __forceinline__ void tr_block8(const float* src, int ldw, unsigned char* dst  , int Kb, float sc, LAS float* scr, int lane) {
;     const int kr = lane >> 3, c4 = lane & 7;
;     f32x4 v[8];
; #pragma unroll
;     for (int i = 0; i < 8; ++i) v[i] = *(const f32x4*)(src + (size_t)(8 * i + kr) * ldw + 4 * c4);
; #pragma unroll
;     for (int i = 0; i < 8; ++i) { LAS float* d = scr + (8 * i + kr) * 33 + 4 * c4; d[0] = v[i].x; d[1] = v[i].y; d[2] = v[i].z; d[3] = v[i].w; }
;     asm volatile("s_waitcnt lgkmcnt(0)" ::: "memory");
;     const int c = lane & 7;
; #pragma unroll
;     for (int j = 0; j < 4; ++j) { const int n = (lane >> 3) + 8 * j; const LAS float* s = scr + (8 * c) * 33 + n;
;         int w0 = 0, w1 = 0; w0 = __builtin_amdgcn_cvt_pk_fp8_f32(s[0 * 33] * sc, s[1 * 33] * sc, w0, false); w0 = __builtin_amdgcn_cvt_pk_fp8_f32(s[2 * 33] * sc, s[3 * 33] * sc, w0, true);
;         w1 = __builtin_amdgcn_cvt_pk_fp8_f32(s[4 * 33] * sc, s[5 * 33] * sc, w1, false); w1 = __builtin_amdgcn_cvt_pk_fp8_f32(s[6 * 33] * sc, s[7 * 33] * sc, w1, true);
;         *(v2u*)(dst + (size_t)n * Kb + 8 * c) = (v2u){(unsigned)w0, (unsigned)w1}; }
;     asm volatile("s_waitcnt lgkmcnt(0)" ::: "memory");
; template <int SEL> __global__ void __launch_bounds__(NWAVES * 64, 2) fwd_kernel(Args args) {
;     ...
;             { const int e = r / I_EDN; r -= e * I_EDN; tr_seg8<0>(in[20] + (size_t)e * DFFE * 1024, 1024, DFFE, 0, 1024, (unsigned char*)q_Wedn_t + (size_t)e * 1024 * DFFE, 0, 0, W8_SCALE, scr, r, lane); }
.LBB0_10:
	s_add_i32 s4, s3, 0x9c80
	s_cmpk_gt_i32 s4, 0x1bff
	s_mov_b64 s[18:19], -1
	s_cbranch_scc0 .LBB0_24
	s_cmpk_gt_u32 s4, 0x26ff
	s_cbranch_scc0 .LBB0_21
	s_cmpk_gt_u32 s4, 0x2c7f
	s_cbranch_scc0 .LBB0_18
	s_cmpk_gt_u32 s4, 0x9c7f
	s_cbranch_scc0 .LBB0_15
	s_and_b32 s18, s3, 0xffff
	s_mul_hi_u32 s18, s18, 0x24924a
	s_bfe_u32 s19, s3, 0x80008
	s_mul_i32 s18, s18, 0xf900
	s_mulk_i32 s19, 0x2493
	s_lshr_b32 s52, s19, 16
	s_add_i32 s53, s3, s18
	s_mov_b64 s[18:19], s[0:1]
	s_load_dwordx2 s[18:19], s[18:19], 0xa0
	s_mov_b64 s[20:21], s[0:1]
	s_load_dwordx2 s[20:21], s[20:21], 0xc0
	s_mul_i32 s54, s52, 0xe00000
	s_waitcnt lgkmcnt(0)
	s_add_u32 s54, s18, s54
	s_addc_u32 s55, s19, 0
	s_mul_i32 s52, s52, 0x380000
	s_add_u32 s56, s20, s52
	s_sext_i32_i16 s18, s53
	s_addc_u32 s57, s21, 0
	s_bfe_u32 s18, s18, 0x5001a
	s_add_i32 s18, s53, s18
	s_sext_i32_i16 s19, s18
	s_and_b32 s18, s18, 0xffe0
	s_sub_i32 s18, s53, s18
	s_sext_i32_i16 s58, s18
	s_lshl_b32 s18, s19, 1
	s_andn2_b32 s18, s18, 63
	s_ashr_i32 s19, s18, 31
	s_lshl_b32 s20, s58, 5
	s_lshl_b64 s[52:53], s[18:19], 12
	s_add_u32 s54, s54, s52
	s_addc_u32 s55, s55, s53
	s_ashr_i32 s21, s20, 31
	s_lshl_b64 s[52:53], s[20:21], 2
	s_add_u32 s52, s54, s52
	s_addc_u32 s53, s55, s53
	v_lshl_add_u64 v[92:93], s[52:53], 0, v[2:3]
	v_mov_b32_e32 v59, v3
	v_mov_b32_e32 v61, v3
	v_mov_b32_e32 v63, v3
	v_lshlrev_b32_e32 v74, 2, v10
	v_mov_b32_e32 v75, v3
	v_lshlrev_b32_e32 v80, 2, v12
	v_mov_b32_e32 v81, v3
	v_lshlrev_b32_e32 v82, 2, v14
	v_mov_b32_e32 v83, v3
	v_lshl_add_u64 v[64:65], v[92:93], 0, v[58:59]
	v_lshl_add_u64 v[68:69], v[92:93], 0, v[60:61]
	v_lshl_add_u64 v[72:73], v[92:93], 0, v[62:63]
	v_lshl_add_u64 v[76:77], v[92:93], 0, v[74:75]
	v_lshl_add_u64 v[80:81], v[92:93], 0, v[80:81]
	v_lshl_add_u64 v[84:85], v[92:93], 0, v[82:83]
	global_load_dwordx4 v[64:67], v[64:65], off nt
	s_nop 0
	global_load_dwordx4 v[68:71], v[68:69], off nt
	s_nop 0
	global_load_dwordx4 v[72:75], v[72:73], off nt
	s_nop 0
	global_load_dwordx4 v[76:79], v[76:77], off nt
	s_nop 0
	global_load_dwordx4 v[80:83], v[80:81], off nt
	s_nop 0
	global_load_dwordx4 v[84:87], v[84:85], off nt
	v_lshlrev_b32_e32 v88, 2, v16
	v_mov_b32_e32 v89, v3
	v_lshl_add_u64 v[88:89], v[92:93], 0, v[88:89]
	global_load_dwordx4 v[88:91], v[88:89], off nt
	v_lshlrev_b32_e32 v94, 2, v18
	v_mov_b32_e32 v95, v3
	v_lshl_add_u64 v[92:93], v[92:93], 0, v[94:95]
	global_load_dwordx4 v[92:95], v[92:93], off nt
	v_add_u32_e32 v19, v13, v15
	v_add_u32_e32 v27, 0x420, v19
	v_add_u32_e32 v29, 0x428, v19
	v_add_u32_e32 v31, 0x840, v19
	v_add_u32_e32 v33, 0x848, v19
	v_add_u32_e32 v35, 0xc60, v19
	v_add_u32_e32 v37, 0xc68, v19
	v_add_u32_e32 v39, 0x1080, v19
	v_add_u32_e32 v41, 0x1088, v19
	v_add_u32_e32 v43, 0x14a0, v19
	v_add_u32_e32 v45, 0x14a8, v19
	v_add_u32_e32 v47, 0x18c0, v19
	v_add_u32_e32 v49, 0x18c8, v19
	v_add_u32_e32 v51, 0x1ce0, v19
	v_add_u32_e32 v53, 0x1ce8, v19
	v_mov_b32_e32 v96, v3
	v_mov_b32_e32 v97, v3
	s_mul_i32 s58, s58, 0x1c000
	s_mul_hi_i32 s20, s20, 0xe00
	s_add_u32 s21, s56, s58
	s_addc_u32 s20, s57, s20
	s_add_u32 s18, s21, s18
	s_addc_u32 s19, s20, s19
	s_waitcnt vmcnt(7)
	ds_write2_b32 v19, v64, v65 offset1:1
	ds_write2_b32 v19, v66, v67 offset0:2 offset1:3
	s_waitcnt vmcnt(6)
	ds_write2_b32 v27, v68, v69 offset1:1
	ds_write2_b32 v29, v70, v71 offset1:1
	s_waitcnt vmcnt(5)
	ds_write2_b32 v31, v72, v73 offset1:1
	ds_write2_b32 v33, v74, v75 offset1:1
	s_waitcnt vmcnt(4)
	ds_write2_b32 v35, v76, v77 offset1:1
	ds_write2_b32 v37, v78, v79 offset1:1
	s_waitcnt vmcnt(3)
	ds_write2_b32 v39, v80, v81 offset1:1
	ds_write2_b32 v41, v82, v83 offset1:1
	s_waitcnt vmcnt(2)
	ds_write2_b32 v43, v84, v85 offset1:1
	ds_write2_b32 v45, v86, v87 offset1:1
	s_waitcnt vmcnt(1)
	ds_write2_b32 v47, v88, v89 offset1:1
	ds_write2_b32 v49, v90, v91 offset1:1
	s_waitcnt vmcnt(0)
	ds_write2_b32 v51, v92, v93 offset1:1
	ds_write2_b32 v53, v94, v95 offset1:1
	s_waitcnt lgkmcnt(0)
	ds_read2_b32 v[64:65], v17 offset1:8
	ds_read2_b32 v[66:67], v17 offset0:33 offset1:41
	ds_read2_b32 v[70:71], v17 offset0:66 offset1:74
	ds_read2_b32 v[72:73], v17 offset0:99 offset1:107
	ds_read2_b32 v[74:75], v17 offset0:132 offset1:140
	ds_read2_b32 v[76:77], v17 offset0:165 offset1:173
	ds_read2_b32 v[78:79], v17 offset0:198 offset1:206
	ds_read2_b32 v[80:81], v17 offset0:231 offset1:239
	s_waitcnt lgkmcnt(7)
	v_mul_f32_e32 v19, 0x42800000, v64
	s_waitcnt lgkmcnt(6)
	v_mul_f32_e32 v27, 0x42800000, v66
	v_cvt_pk_fp8_f32 v96, v19, v27
	s_waitcnt lgkmcnt(3)
	v_mul_f32_e32 v29, 0x42800000, v74
	s_waitcnt lgkmcnt(2)
	v_mul_f32_e32 v31, 0x42800000, v76
	v_cvt_pk_fp8_f32 v97, v29, v31
	v_mul_f32_e32 v19, 0x42800000, v70
	v_mul_f32_e32 v27, 0x42800000, v72
	v_cvt_pk_fp8_f32 v96, v19, v27 op_sel:[0,0,1]
	s_waitcnt lgkmcnt(1)
	v_mul_f32_e32 v19, 0x42800000, v78
	s_waitcnt lgkmcnt(0)
	v_mul_f32_e32 v27, 0x42800000, v80
	v_cvt_pk_fp8_f32 v97, v19, v27 op_sel:[0,0,1]
	v_mul_f32_e32 v19, 0x42800000, v65
	v_mul_f32_e32 v27, 0x42800000, v67
	v_mov_b32_e32 v64, v3
	v_cvt_pk_fp8_f32 v64, v19, v27
	v_mul_f32_e32 v29, 0x42800000, v75
	v_mul_f32_e32 v31, 0x42800000, v77
	v_mov_b32_e32 v65, v3
	v_cvt_pk_fp8_f32 v65, v29, v31
	v_lshl_add_u64 v[68:69], s[18:19], 0, v[20:21]
	v_mul_f32_e32 v19, 0x42800000, v71
	v_mul_f32_e32 v27, 0x42800000, v73
	v_lshl_add_u64 v[68:69], v[68:69], 0, v[22:23]
	v_cvt_pk_fp8_f32 v64, v19, v27 op_sel:[0,0,1]
	v_mul_f32_e32 v19, 0x42800000, v79
	v_mul_f32_e32 v27, 0x42800000, v81
	v_add_co_u32_e32 v82, vcc, s29, v68
	v_cvt_pk_fp8_f32 v65, v19, v27 op_sel:[0,0,1]
	s_nop 0
	v_addc_co_u32_e32 v83, vcc, 0, v69, vcc
	v_add_co_u32_e32 v72, vcc, s31, v68
	global_store_dwordx2 v[82:83], v[96:97], off
	s_nop 0
	v_addc_co_u32_e32 v73, vcc, 0, v69, vcc
	ds_read2_b32 v[66:67], v17 offset0:16 offset1:24
	ds_read2_b32 v[70:71], v17 offset0:49 offset1:57
	global_store_dwordx2 v[72:73], v[64:65], off
	ds_read2_b32 v[72:73], v17 offset0:82 offset1:90
	ds_read2_b32 v[74:75], v17 offset0:115 offset1:123
	ds_read2_b32 v[76:77], v17 offset0:148 offset1:156
	ds_read2_b32 v[78:79], v17 offset0:181 offset1:189
	v_mov_b32_e32 v64, v3
	s_waitcnt lgkmcnt(5)
; #define in KArgIn()
; __device__ __forceinline__ void tr_block8(const float* src, int ldw, unsigned char* dst  , int Kb, float sc, LAS float* scr, int lane) {
;     const int kr = lane >> 3, c4 = lane & 7;
;     f32x4 v[8];
; #pragma unroll
;     for (int i = 0; i < 8; ++i) v[i] = *(const f32x4*)(src + (size_t)(8 * i + kr) * ldw + 4 * c4);
; #pragma unroll
;     for (int i = 0; i < 8; ++i) { LAS float* d = scr + (8 * i + kr) * 33 + 4 * c4; d[0] = v[i].x; d[1] = v[i].y; d[2] = v[i].z; d[3] = v[i].w; }
;     asm volatile("s_waitcnt lgkmcnt(0)" ::: "memory");
;     const int c = lane & 7;
; #pragma unroll
;     for (int j = 0; j < 4; ++j) { const int n = (lane >> 3) + 8 * j; const LAS float* s = scr + (8 * c) * 33 + n;
;         int w0 = 0, w1 = 0; w0 = __builtin_amdgcn_cvt_pk_fp8_f32(s[0 * 33] * sc, s[1 * 33] * sc, w0, false); w0 = __builtin_amdgcn_cvt_pk_fp8_f32(s[2 * 33] * sc, s[3 * 33] * sc, w0, true);
;         w1 = __builtin_amdgcn_cvt_pk_fp8_f32(s[4 * 33] * sc, s[5 * 33] * sc, w1, false); w1 = __builtin_amdgcn_cvt_pk_fp8_f32(s[6 * 33] * sc, s[7 * 33] * sc, w1, true);
;         *(v2u*)(dst + (size_t)n * Kb + 8 * c) = (v2u){(unsigned)w0, (unsigned)w1}; }
;     asm volatile("s_waitcnt lgkmcnt(0)" ::: "memory");
; }
; template <int MAP> __device__ __forceinline__ void tr_seg8(const float* W, int ldw, int K, int c0, int ncols, unsigned char* WT, int row_off, int F, float sc, LAS float* scr, int item, int lane) {
;     const int nblk = ncols / 32, kb = item / nblk, nb = item % nblk, k0 = 64 * kb, n0 = 32 * nb;
;     int drow;
;     if (MAP == 0) drow = row_off + n0; else { int c = n0; const int up = c >= F; if (up) c -= F; drow = row_off + 256 * (c / 128) + 128 * up + (c % 128); }
;     tr_block8(W + (size_t)k0 * ldw + c0 + n0, ldw, WT + (size_t)drow * K + k0, K, sc, scr, lane);
; }
; template <int SEL> __global__ void __launch_bounds__(NWAVES * 64, 2) fwd_kernel(Args args) {
;     ...
;             if (r < 8 * I_EGU) { const int e = r / I_EGU; r -= e * I_EGU; tr_seg8<1>(in[19] + (size_t)e * 1024 * 2 * DFFE, 2 * DFFE, 1024, 0, 2 * DFFE, (unsigned char*)q_Wegu_t + (size_t)e * 2 * DFFE * 1024, 0, DFFE, W8_SCALE, scr, r, lane); continue; } r -= 8 * I_EGU;
;             { const int e = r / I_EDN; r -= e * I_EDN; tr_seg8<0>(in[20] + (size_t)e * DFFE * 1024, 1024, DFFE, 0, 1024, (unsigned char*)q_Wedn_t + (size_t)e * 1024 * DFFE, 0, 0, W8_SCALE, scr, r, lane); }
	v_mul_f32_e32 v19, 0x42800000, v66
	s_waitcnt lgkmcnt(4)
	v_mul_f32_e32 v27, 0x42800000, v70
	ds_read2_b32 v[80:81], v17 offset0:214 offset1:222
	ds_read2_b32 v[82:83], v17 offset0:247 offset1:255
	v_cvt_pk_fp8_f32 v64, v19, v27
	s_waitcnt lgkmcnt(3)
	v_mul_f32_e32 v29, 0x42800000, v76
	s_waitcnt lgkmcnt(2)
	v_mul_f32_e32 v31, 0x42800000, v78
	v_mov_b32_e32 v65, v3
	v_cvt_pk_fp8_f32 v65, v29, v31
	v_mul_f32_e32 v19, 0x42800000, v72
	v_mul_f32_e32 v27, 0x42800000, v74
	v_cvt_pk_fp8_f32 v64, v19, v27 op_sel:[0,0,1]
	s_waitcnt lgkmcnt(1)
	v_mul_f32_e32 v19, 0x42800000, v80
	s_waitcnt lgkmcnt(0)
	v_mul_f32_e32 v27, 0x42800000, v82
	v_cvt_pk_fp8_f32 v65, v19, v27 op_sel:[0,0,1]
	v_add_co_u32_e32 v84, vcc, s34, v68
	v_mul_f32_e32 v19, 0x42800000, v67
	s_nop 0
	v_addc_co_u32_e32 v85, vcc, 0, v69, vcc
	global_store_dwordx2 v[84:85], v[64:65], off
	v_mul_f32_e32 v27, 0x42800000, v71
	v_mov_b32_e32 v64, v3
	v_cvt_pk_fp8_f32 v64, v19, v27
	v_mul_f32_e32 v29, 0x42800000, v77
	v_mul_f32_e32 v31, 0x42800000, v79
	v_mov_b32_e32 v65, v3
	v_cvt_pk_fp8_f32 v65, v29, v31
	v_mul_f32_e32 v19, 0x42800000, v73
	v_mul_f32_e32 v27, 0x42800000, v75
	v_cvt_pk_fp8_f32 v64, v19, v27 op_sel:[0,0,1]
	v_mul_f32_e32 v19, 0x42800000, v81
	v_mul_f32_e32 v27, 0x42800000, v83
	v_cvt_pk_fp8_f32 v65, v19, v27 op_sel:[0,0,1]
	v_add_co_u32_e32 v66, vcc, 0xad15000, v68
	s_mov_b64 s[18:19], 0
	s_nop 0
	v_addc_co_u32_e32 v67, vcc, 0, v69, vcc
	global_store_dwordx2 v[66:67], v[64:65], off
	s_waitcnt lgkmcnt(0)
.LBB0_15:
	s_andn2_b64 vcc, exec, s[18:19]
	s_cbranch_vccnz .LBB0_17
	s_and_b32 s18, 0xffff, s22
	s_mul_hi_u32 s18, s18, 0x124925
	s_mul_i32 s18, s18, 0xf200
	s_add_i32 s19, s3, 0x7000
	s_bfe_u32 s20, s19, 0x100009
	s_add_i32 s53, s19, s18
	s_mov_b64 s[18:19], s[0:1]
	s_mulk_i32 s20, 0x2493
	s_lshr_b32 s52, s20, 16
	s_load_dwordx2 s[18:19], s[18:19], 0x98
	s_mov_b64 s[20:21], s[0:1]
	s_load_dwordx2 s[20:21], s[20:21], 0xc0
	s_mul_i32 s54, s52, 0x1c00000
	s_waitcnt lgkmcnt(0)
	s_add_u32 s54, s18, s54
	s_addc_u32 s19, s19, 0
	s_mul_i32 s52, s52, 0x700000
	s_sext_i32_i16 s18, s53
	s_add_u32 s52, s20, s52
	s_mulk_i32 s18, 0x4925
	s_addc_u32 s55, s21, 0
	s_lshr_b32 s20, s18, 31
	s_ashr_i32 s18, s18, 22
	s_add_i32 s21, s18, s20
	s_mul_i32 s18, s21, 0xe0
	s_sub_i32 s18, s53, s18
	s_sext_i32_i16 s20, s18
	s_lshl_b32 s18, s20, 5
	s_cmpk_lt_i32 s20, 0x70
	s_cselect_b32 s53, 0, 0xf200
	s_cselect_b32 s20, 0, 0x80
	s_add_i32 s53, s53, s18
	s_sext_i32_i16 s57, s53
	s_bfe_u32 s57, s57, 0x70018
	s_add_i32 s57, s53, s57
	s_sext_i32_i16 s58, s57
	s_and_b32 s57, s57, 0xff80
	s_sub_i32 s53, s53, s57
	s_lshl_b32 s58, s58, 1
	s_sext_i32_i16 s53, s53
	s_lshl_b32 s56, s21, 6
	s_and_b32 s58, s58, 0xffffff00
	s_add_i32 s20, s20, s53
	s_add_i32 s20, s20, s58
	s_ashr_i32 s53, s56, 31
	s_mul_i32 s21, s21, 0x1c0000
	s_mul_hi_i32 s57, s56, 0x7000
	s_add_u32 s21, s54, s21
	s_addc_u32 s54, s19, s57
	s_ashr_i32 s19, s18, 31
	s_lshl_b64 s[18:19], s[18:19], 2
	s_add_u32 s18, s21, s18
	s_addc_u32 s19, s54, s19
	v_lshl_add_u64 v[92:93], s[18:19], 0, v[2:3]
	v_mov_b32_e32 v43, v3
	v_lshl_add_u64 v[80:81], v[92:93], 0, v[42:43]
	v_add_co_u32_e32 v68, vcc, s35, v80
	v_mov_b32_e32 v45, v3
	s_nop 0
	v_addc_co_u32_e32 v69, vcc, 0, v81, vcc
	v_add_co_u32_e32 v72, vcc, s36, v80
	global_load_dwordx4 v[64:67], v[80:81], off nt
	s_nop 0
	global_load_dwordx4 v[68:71], v[68:69], off nt
	v_addc_co_u32_e32 v73, vcc, 0, v81, vcc
	v_add_co_u32_e32 v76, vcc, s37, v80
	v_lshl_add_u64 v[84:85], v[92:93], 0, v[44:45]
	s_nop 0
	v_addc_co_u32_e32 v77, vcc, 0, v81, vcc
	v_add_co_u32_e32 v80, vcc, s38, v80
	v_mov_b32_e32 v47, v3
	s_nop 0
	v_addc_co_u32_e32 v81, vcc, 0, v81, vcc
	global_load_dwordx4 v[72:75], v[72:73], off nt
	s_nop 0
	global_load_dwordx4 v[76:79], v[76:77], off nt
	s_nop 0
	global_load_dwordx4 v[80:83], v[80:81], off nt
	s_nop 0
	global_load_dwordx4 v[84:87], v[84:85], off nt
	v_lshl_add_u64 v[88:89], v[92:93], 0, v[46:47]
	v_mov_b32_e32 v49, v3
	global_load_dwordx4 v[88:91], v[88:89], off nt
	v_lshl_add_u64 v[92:93], v[92:93], 0, v[48:49]
	global_load_dwordx4 v[92:95], v[92:93], off nt
	v_add_u32_e32 v19, v13, v15
	v_add_u32_e32 v27, 0x420, v19
	v_add_u32_e32 v29, 0x428, v19
	v_add_u32_e32 v31, 0x840, v19
	v_add_u32_e32 v33, 0x848, v19
	v_add_u32_e32 v35, 0xc60, v19
	v_add_u32_e32 v37, 0xc68, v19
	v_add_u32_e32 v39, 0x1080, v19
	v_add_u32_e32 v41, 0x1088, v19
	v_add_u32_e32 v43, 0x14a0, v19
	v_add_u32_e32 v45, 0x14a8, v19
	v_add_u32_e32 v47, 0x18c0, v19
	s_ashr_i32 s21, s20, 31
	s_lshl_b64 s[18:19], s[20:21], 10
	s_add_u32 s18, s52, s18
	s_addc_u32 s19, s55, s19
	s_add_u32 s18, s18, s56
	s_addc_u32 s19, s19, s53
	s_waitcnt vmcnt(7)
; #define LAS __attribute__((address_space(3)))
; __device__ __forceinline__ void tr_block8(const float* src, int ldw, unsigned char* dst  , int Kb, float sc, LAS float* scr, int lane) {
;     ...
; #pragma unroll
;     for (int i = 0; i < 8; ++i) { LAS float* d = scr + (8 * i + kr) * 33 + 4 * c4; d[0] = v[i].x; d[1] = v[i].y; d[2] = v[i].z; d[3] = v[i].w; }
;     asm volatile("s_waitcnt lgkmcnt(0)" ::: "memory");
;     const int c = lane & 7;
; #pragma unroll
;     for (int j = 0; j < 4; ++j) { const int n = (lane >> 3) + 8 * j; const LAS float* s = scr + (8 * c) * 33 + n;
;         int w0 = 0, w1 = 0; w0 = __builtin_amdgcn_cvt_pk_fp8_f32(s[0 * 33] * sc, s[1 * 33] * sc, w0, false); w0 = __builtin_amdgcn_cvt_pk_fp8_f32(s[2 * 33] * sc, s[3 * 33] * sc, w0, true);
;         w1 = __builtin_amdgcn_cvt_pk_fp8_f32(s[4 * 33] * sc, s[5 * 33] * sc, w1, false); w1 = __builtin_amdgcn_cvt_pk_fp8_f32(s[6 * 33] * sc, s[7 * 33] * sc, w1, true);
;         *(v2u*)(dst + (size_t)n * Kb + 8 * c) = (v2u){(unsigned)w0, (unsigned)w1}; }
;     asm volatile("s_waitcnt lgkmcnt(0)" ::: "memory");
	ds_write2_b32 v19, v64, v65 offset1:1
	ds_write2_b32 v19, v66, v67 offset0:2 offset1:3
	s_waitcnt vmcnt(6)
	ds_write2_b32 v27, v68, v69 offset1:1
	ds_write2_b32 v29, v70, v71 offset1:1
	s_waitcnt vmcnt(5)
	ds_write2_b32 v31, v72, v73 offset1:1
	ds_write2_b32 v33, v74, v75 offset1:1
	s_waitcnt vmcnt(4)
	ds_write2_b32 v35, v76, v77 offset1:1
	ds_write2_b32 v37, v78, v79 offset1:1
	s_waitcnt vmcnt(3)
	ds_write2_b32 v39, v80, v81 offset1:1
	ds_write2_b32 v41, v82, v83 offset1:1
	s_waitcnt vmcnt(2)
	ds_write2_b32 v43, v84, v85 offset1:1
	ds_write2_b32 v45, v86, v87 offset1:1
	s_waitcnt vmcnt(1)
	ds_write2_b32 v47, v88, v89 offset1:1
	v_add_u32_e32 v27, 0x18c8, v19
	v_mov_b32_e32 v70, v3
	ds_write2_b32 v27, v90, v91 offset1:1
	v_add_u32_e32 v27, 0x1ce0, v19
	v_add_u32_e32 v19, 0x1ce8, v19
	s_waitcnt vmcnt(0)
	ds_write2_b32 v27, v92, v93 offset1:1
	ds_write2_b32 v19, v94, v95 offset1:1
	s_waitcnt lgkmcnt(0)
	ds_read2_b32 v[64:65], v17 offset1:8
	ds_read2_b32 v[66:67], v17 offset0:33 offset1:41
	ds_read2_b32 v[72:73], v17 offset0:66 offset1:74
	ds_read2_b32 v[74:75], v17 offset0:99 offset1:107
	ds_read2_b32 v[76:77], v17 offset0:132 offset1:140
	ds_read2_b32 v[78:79], v17 offset0:165 offset1:173
	ds_read2_b32 v[80:81], v17 offset0:198 offset1:206
	ds_read2_b32 v[82:83], v17 offset0:231 offset1:239
	v_mov_b32_e32 v71, v3
	s_waitcnt lgkmcnt(7)
	v_mul_f32_e32 v19, 0x42800000, v64
	s_waitcnt lgkmcnt(6)
	v_mul_f32_e32 v27, 0x42800000, v66
	v_cvt_pk_fp8_f32 v70, v19, v27
	s_waitcnt lgkmcnt(3)
	v_mul_f32_e32 v29, 0x42800000, v76
	s_waitcnt lgkmcnt(2)
	v_mul_f32_e32 v31, 0x42800000, v78
	v_cvt_pk_fp8_f32 v71, v29, v31
	v_mul_f32_e32 v19, 0x42800000, v72
	v_mul_f32_e32 v27, 0x42800000, v74
	v_cvt_pk_fp8_f32 v70, v19, v27 op_sel:[0,0,1]
	s_waitcnt lgkmcnt(1)
	v_mul_f32_e32 v19, 0x42800000, v80
	s_waitcnt lgkmcnt(0)
	v_mul_f32_e32 v27, 0x42800000, v82
	v_cvt_pk_fp8_f32 v71, v19, v27 op_sel:[0,0,1]
	v_mul_f32_e32 v19, 0x42800000, v65
	v_mul_f32_e32 v27, 0x42800000, v67
	v_mov_b32_e32 v64, v3
	v_cvt_pk_fp8_f32 v64, v19, v27
	v_mul_f32_e32 v29, 0x42800000, v77
	v_mul_f32_e32 v31, 0x42800000, v79
	v_mov_b32_e32 v65, v3
	v_cvt_pk_fp8_f32 v65, v29, v31
	v_mul_f32_e32 v19, 0x42800000, v73
	v_mul_f32_e32 v27, 0x42800000, v75
	v_cvt_pk_fp8_f32 v64, v19, v27 op_sel:[0,0,1]
	v_mul_f32_e32 v19, 0x42800000, v81
	v_mul_f32_e32 v27, 0x42800000, v83
	v_lshl_add_u64 v[68:69], s[18:19], 0, v[20:21]
	v_cvt_pk_fp8_f32 v65, v19, v27 op_sel:[0,0,1]
	v_lshl_add_u64 v[68:69], v[68:69], 0, s[6:7]
	v_lshl_add_u64 v[84:85], v[68:69], 0, v[4:5]
	ds_read2_b32 v[66:67], v17 offset0:16 offset1:24
	ds_read2_b32 v[72:73], v17 offset0:49 offset1:57
	global_store_dwordx2 v[84:85], v[70:71], off
	v_lshl_add_u64 v[70:71], v[68:69], 0, v[6:7]
	global_store_dwordx2 v[70:71], v[64:65], off
	ds_read2_b32 v[70:71], v17 offset0:82 offset1:90
	ds_read2_b32 v[74:75], v17 offset0:115 offset1:123
	ds_read2_b32 v[76:77], v17 offset0:148 offset1:156
	ds_read2_b32 v[78:79], v17 offset0:181 offset1:189
	s_waitcnt lgkmcnt(5)
	v_mul_f32_e32 v19, 0x42800000, v66
	s_waitcnt lgkmcnt(4)
	v_mul_f32_e32 v27, 0x42800000, v72
	v_mov_b32_e32 v64, v3
	ds_read2_b32 v[80:81], v17 offset0:214 offset1:222
	ds_read2_b32 v[82:83], v17 offset0:247 offset1:255
	v_cvt_pk_fp8_f32 v64, v19, v27
	s_waitcnt lgkmcnt(3)
	v_mul_f32_e32 v29, 0x42800000, v76
	s_waitcnt lgkmcnt(2)
	v_mul_f32_e32 v31, 0x42800000, v78
	v_mov_b32_e32 v65, v3
	v_cvt_pk_fp8_f32 v65, v29, v31
	v_mul_f32_e32 v19, 0x42800000, v70
	v_mul_f32_e32 v27, 0x42800000, v74
	v_cvt_pk_fp8_f32 v64, v19, v27 op_sel:[0,0,1]
	s_waitcnt lgkmcnt(1)
	v_mul_f32_e32 v19, 0x42800000, v80
	s_waitcnt lgkmcnt(0)
	v_mul_f32_e32 v27, 0x42800000, v82
	v_cvt_pk_fp8_f32 v65, v19, v27 op_sel:[0,0,1]
	v_mul_f32_e32 v19, 0x42800000, v67
	v_mul_f32_e32 v27, 0x42800000, v73
	v_mov_b32_e32 v66, v3
	v_cvt_pk_fp8_f32 v66, v19, v27
	v_mul_f32_e32 v29, 0x42800000, v77
	v_mul_f32_e32 v31, 0x42800000, v79
	v_mov_b32_e32 v67, v3
	v_cvt_pk_fp8_f32 v67, v29, v31
	v_mul_f32_e32 v19, 0x42800000, v71
	v_mul_f32_e32 v27, 0x42800000, v75
	v_cvt_pk_fp8_f32 v66, v19, v27 op_sel:[0,0,1]
	v_mul_f32_e32 v19, 0x42800000, v81
	v_mul_f32_e32 v27, 0x42800000, v83
	v_cvt_pk_fp8_f32 v67, v19, v27 op_sel:[0,0,1]
	v_lshl_add_u64 v[70:71], v[68:69], 0, v[8:9]
	global_store_dwordx2 v[70:71], v[64:65], off
	v_lshl_add_u64 v[64:65], v[68:69], 0, v[10:11]
	global_store_dwordx2 v[64:65], v[66:67], off
	s_waitcnt lgkmcnt(0)

; #define LAS __attribute__((address_space(3)))
; #define in KArgIn()
; __device__ __forceinline__ void tr_block8(const float* src, int ldw, unsigned char* dst  , int Kb, float sc, LAS float* scr, int lane) {
;     const int kr = lane >> 3, c4 = lane & 7;
;     f32x4 v[8];
; #pragma unroll
;     for (int i = 0; i < 8; ++i) v[i] = *(const f32x4*)(src + (size_t)(8 * i + kr) * ldw + 4 * c4);
; #pragma unroll
;     for (int i = 0; i < 8; ++i) { LAS float* d = scr + (8 * i + kr) * 33 + 4 * c4; d[0] = v[i].x; d[1] = v[i].y; d[2] = v[i].z; d[3] = v[i].w; }
;     asm volatile("s_waitcnt lgkmcnt(0)" ::: "memory");
;     const int c = lane & 7;
; #pragma unroll
;     for (int j = 0; j < 4; ++j) { const int n = (lane >> 3) + 8 * j; const LAS float* s = scr + (8 * c) * 33 + n;
;         int w0 = 0, w1 = 0; w0 = __builtin_amdgcn_cvt_pk_fp8_f32(s[0 * 33] * sc, s[1 * 33] * sc, w0, false); w0 = __builtin_amdgcn_cvt_pk_fp8_f32(s[2 * 33] * sc, s[3 * 33] * sc, w0, true);
;         w1 = __builtin_amdgcn_cvt_pk_fp8_f32(s[4 * 33] * sc, s[5 * 33] * sc, w1, false); w1 = __builtin_amdgcn_cvt_pk_fp8_f32(s[6 * 33] * sc, s[7 * 33] * sc, w1, true);
;         *(v2u*)(dst + (size_t)n * Kb + 8 * c) = (v2u){(unsigned)w0, (unsigned)w1}; }
;     asm volatile("s_waitcnt lgkmcnt(0)" ::: "memory");
; template <int SEL> __global__ void __launch_bounds__(NWAVES * 64, 2) fwd_kernel(Args args) {
;     ...
;             if (r < I_DN) { if constexpr (DENSE_FP8 == 2) tr_seg8<0>(in[17], 1024, DFF, 0, 1024, (unsigned char*)q_Wdn_t, 0, 0, W8_SCALE, scr, r, lane); else tr_seg<0>(in[17], 1024, DFF, 0, 1024, q_Wdn_t, 0, 0, scr, r, lane); continue; } r -= I_DN;
.LBB0_18:
	s_andn2_b64 vcc, exec, s[18:19]
	s_cbranch_vccnz .LBB0_20
	s_mov_b64 s[18:19], s[0:1]
	s_load_dwordx2 s[20:21], s[18:19], 0x88
	s_add_i32 s52, s23, 0x1b200
	s_and_b32 s52, s52, 0x1ffc0
	s_and_b32 s53, s27, 0x3e0
	s_lshl_b32 s54, s52, 12
	s_waitcnt lgkmcnt(0)
	s_add_u32 s20, s20, s54
	s_addc_u32 s21, s21, 0
	s_lshl_b32 s54, s53, 2
	s_add_u32 s20, s20, s54
	s_addc_u32 s21, s21, 0
	v_lshl_add_u64 v[92:93], s[20:21], 0, v[2:3]
	v_mov_b32_e32 v59, v3
	v_mov_b32_e32 v61, v3
	v_mov_b32_e32 v63, v3
	v_lshlrev_b32_e32 v74, 2, v10
	v_mov_b32_e32 v75, v3
	v_lshlrev_b32_e32 v80, 2, v12
	v_mov_b32_e32 v81, v3
	v_lshlrev_b32_e32 v82, 2, v14
	v_mov_b32_e32 v83, v3
	s_mov_b64 s[18:19], s[0:1]
	v_lshl_add_u64 v[64:65], v[92:93], 0, v[58:59]
	v_lshl_add_u64 v[68:69], v[92:93], 0, v[60:61]
	v_lshl_add_u64 v[72:73], v[92:93], 0, v[62:63]
	v_lshl_add_u64 v[76:77], v[92:93], 0, v[74:75]
	v_lshl_add_u64 v[80:81], v[92:93], 0, v[80:81]
	v_lshl_add_u64 v[84:85], v[92:93], 0, v[82:83]
	global_load_dwordx4 v[64:67], v[64:65], off nt
	s_nop 0
	global_load_dwordx4 v[68:71], v[68:69], off nt
	s_nop 0
	global_load_dwordx4 v[72:75], v[72:73], off nt
	s_nop 0
	global_load_dwordx4 v[76:79], v[76:77], off nt
	s_nop 0
	global_load_dwordx4 v[80:83], v[80:81], off nt
	s_nop 0
	global_load_dwordx4 v[84:87], v[84:85], off nt
	v_lshlrev_b32_e32 v88, 2, v16
	v_mov_b32_e32 v89, v3
	v_lshl_add_u64 v[88:89], v[92:93], 0, v[88:89]
	global_load_dwordx4 v[88:91], v[88:89], off nt
	v_lshlrev_b32_e32 v94, 2, v18
	v_mov_b32_e32 v95, v3
	v_lshl_add_u64 v[92:93], v[92:93], 0, v[94:95]
	global_load_dwordx4 v[92:95], v[92:93], off nt
	v_add_u32_e32 v19, v13, v15
	v_add_u32_e32 v27, 0x420, v19
	v_add_u32_e32 v29, 0x428, v19
	v_add_u32_e32 v31, 0x840, v19
	v_add_u32_e32 v33, 0x848, v19
	v_add_u32_e32 v35, 0xc60, v19
	v_add_u32_e32 v37, 0xc68, v19
	v_add_u32_e32 v39, 0x1080, v19
	v_add_u32_e32 v41, 0x1088, v19
	v_add_u32_e32 v43, 0x14a0, v19
	v_add_u32_e32 v45, 0x14a8, v19
	s_load_dwordx2 s[18:19], s[18:19], 0xc0
	v_add_u32_e32 v47, 0x18c0, v19
	v_add_u32_e32 v49, 0x18c8, v19
	v_add_u32_e32 v51, 0x1ce0, v19
	v_add_u32_e32 v53, 0x1ce8, v19
	v_mov_b32_e32 v97, v3
	v_mov_b32_e32 v96, v3
	s_mulk_i32 s53, 0xb00
	s_waitcnt lgkmcnt(0)
	s_add_u32 s18, s18, s53
	s_addc_u32 s19, s19, 0
	s_add_u32 s18, s18, s52
	s_addc_u32 s19, s19, 0
	v_lshl_add_u64 v[98:99], s[18:19], 0, v[20:21]
	v_lshl_add_u64 v[98:99], v[98:99], 0, v[24:25]
	s_waitcnt vmcnt(7)
	ds_write2_b32 v19, v64, v65 offset1:1
	ds_write2_b32 v19, v66, v67 offset0:2 offset1:3
	s_waitcnt vmcnt(6)
	ds_write2_b32 v27, v68, v69 offset1:1
	ds_write2_b32 v29, v70, v71 offset1:1
	s_waitcnt vmcnt(5)
	ds_write2_b32 v31, v72, v73 offset1:1
	ds_write2_b32 v33, v74, v75 offset1:1
	s_waitcnt vmcnt(4)
	ds_write2_b32 v35, v76, v77 offset1:1
	ds_write2_b32 v37, v78, v79 offset1:1
	s_waitcnt vmcnt(3)
	ds_write2_b32 v39, v80, v81 offset1:1
	ds_write2_b32 v41, v82, v83 offset1:1
	s_waitcnt vmcnt(2)
	ds_write2_b32 v43, v84, v85 offset1:1
	ds_write2_b32 v45, v86, v87 offset1:1
	s_waitcnt vmcnt(1)
	ds_write2_b32 v47, v88, v89 offset1:1
	ds_write2_b32 v49, v90, v91 offset1:1
	s_waitcnt vmcnt(0)
	ds_write2_b32 v51, v92, v93 offset1:1
	ds_write2_b32 v53, v94, v95 offset1:1
	s_waitcnt lgkmcnt(0)
	ds_read2_b32 v[64:65], v17 offset1:8
	ds_read2_b32 v[66:67], v17 offset0:33 offset1:41
	ds_read2_b32 v[68:69], v17 offset0:66 offset1:74
	ds_read2_b32 v[70:71], v17 offset0:99 offset1:107
	ds_read2_b32 v[72:73], v17 offset0:132 offset1:140
	ds_read2_b32 v[74:75], v17 offset0:165 offset1:173
	ds_read2_b32 v[76:77], v17 offset0:198 offset1:206
	ds_read2_b32 v[78:79], v17 offset0:231 offset1:239
	s_waitcnt lgkmcnt(7)
	v_mul_f32_e32 v19, 0x42800000, v64
	s_waitcnt lgkmcnt(3)
	v_mul_f32_e32 v33, 0x42800000, v72
	s_waitcnt lgkmcnt(2)
	v_mul_f32_e32 v35, 0x42800000, v74
	v_mul_f32_e32 v27, 0x42800000, v66
	v_cvt_pk_fp8_f32 v97, v33, v35
	v_cvt_pk_fp8_f32 v96, v19, v27
	s_waitcnt lgkmcnt(1)
	v_mul_f32_e32 v19, 0x42800000, v76
	s_waitcnt lgkmcnt(0)
	v_mul_f32_e32 v27, 0x42800000, v78
	v_mul_f32_e32 v29, 0x42800000, v68
	v_mul_f32_e32 v31, 0x42800000, v70
	v_cvt_pk_fp8_f32 v97, v19, v27 op_sel:[0,0,1]
	v_mul_f32_e32 v19, 0x42800000, v65
	v_mul_f32_e32 v27, 0x42800000, v67
	v_mov_b32_e32 v64, v3
	v_cvt_pk_fp8_f32 v96, v29, v31 op_sel:[0,0,1]
	v_cvt_pk_fp8_f32 v64, v19, v27
	v_mul_f32_e32 v29, 0x42800000, v73
	v_mul_f32_e32 v31, 0x42800000, v75
	v_mov_b32_e32 v65, v3
	v_cvt_pk_fp8_f32 v65, v29, v31
	v_mul_f32_e32 v19, 0x42800000, v69
	v_mul_f32_e32 v27, 0x42800000, v71
	v_cvt_pk_fp8_f32 v64, v19, v27 op_sel:[0,0,1]
	v_mul_f32_e32 v19, 0x42800000, v77
	v_mul_f32_e32 v27, 0x42800000, v79
	v_add_co_u32_e32 v80, vcc, s39, v98
	v_cvt_pk_fp8_f32 v65, v19, v27 op_sel:[0,0,1]
	s_nop 0
	v_addc_co_u32_e32 v81, vcc, 0, v99, vcc
	v_add_co_u32_e32 v70, vcc, s40, v98
	global_store_dwordx2 v[80:81], v[96:97], off
	s_nop 0
	v_addc_co_u32_e32 v71, vcc, 0, v99, vcc
	ds_read2_b32 v[66:67], v17 offset0:16 offset1:24
	ds_read2_b32 v[68:69], v17 offset0:49 offset1:57
	global_store_dwordx2 v[70:71], v[64:65], off offset:2048
	ds_read2_b32 v[70:71], v17 offset0:82 offset1:90
	ds_read2_b32 v[72:73], v17 offset0:115 offset1:123
	ds_read2_b32 v[74:75], v17 offset0:148 offset1:156
	ds_read2_b32 v[76:77], v17 offset0:181 offset1:189
	v_mov_b32_e32 v64, v3
	s_waitcnt lgkmcnt(5)
	v_mul_f32_e32 v19, 0x42800000, v66
	s_waitcnt lgkmcnt(4)
	v_mul_f32_e32 v27, 0x42800000, v68
	ds_read2_b32 v[78:79], v17 offset0:214 offset1:222
	ds_read2_b32 v[80:81], v17 offset0:247 offset1:255
	v_cvt_pk_fp8_f32 v64, v19, v27
	s_waitcnt lgkmcnt(3)
	v_mul_f32_e32 v29, 0x42800000, v74
	s_waitcnt lgkmcnt(2)
	v_mul_f32_e32 v31, 0x42800000, v76
	v_mov_b32_e32 v65, v3
	v_cvt_pk_fp8_f32 v65, v29, v31
	v_mul_f32_e32 v19, 0x42800000, v70
	v_mul_f32_e32 v27, 0x42800000, v72
	v_cvt_pk_fp8_f32 v64, v19, v27 op_sel:[0,0,1]
	s_waitcnt lgkmcnt(1)
	v_mul_f32_e32 v19, 0x42800000, v78
	s_waitcnt lgkmcnt(0)
	v_mul_f32_e32 v27, 0x42800000, v80
	v_cvt_pk_fp8_f32 v65, v19, v27 op_sel:[0,0,1]
	v_add_co_u32_e32 v82, vcc, s41, v98
	v_mul_f32_e32 v19, 0x42800000, v67
	s_nop 0
	v_addc_co_u32_e32 v83, vcc, 0, v99, vcc
	global_store_dwordx2 v[82:83], v[64:65], off
	v_mul_f32_e32 v27, 0x42800000, v69
	v_mov_b32_e32 v64, v3
	v_cvt_pk_fp8_f32 v64, v19, v27
	v_mul_f32_e32 v29, 0x42800000, v75
	v_mul_f32_e32 v31, 0x42800000, v77
	v_mov_b32_e32 v65, v3
	v_cvt_pk_fp8_f32 v65, v29, v31
	v_mul_f32_e32 v19, 0x42800000, v71
	v_mul_f32_e32 v27, 0x42800000, v73
	v_cvt_pk_fp8_f32 v64, v19, v27 op_sel:[0,0,1]
	v_mul_f32_e32 v19, 0x42800000, v79
	v_mul_f32_e32 v27, 0x42800000, v81
	v_cvt_pk_fp8_f32 v65, v19, v27 op_sel:[0,0,1]
	v_add_co_u32_e32 v66, vcc, 0x3710000, v98
	s_nop 1
	v_addc_co_u32_e32 v67, vcc, 0, v99, vcc
	global_store_dwordx2 v[66:67], v[64:65], off offset:2048
	s_waitcnt lgkmcnt(0)

; #define in KArgIn()
; template <int SEL> __global__ void __launch_bounds__(NWAVES * 64, 2) fwd_kernel(Args args) {
;     ...
;             if (r < I_GU) { if constexpr (DENSE_FP8 != 0) tr_seg8<1>(in[16], 2 * DFF, 1024, 0, 2 * DFF, (unsigned char*)q_Wgu_t, 0, DFF, W8_SCALE, scr, r, lane); else tr_seg<1>(in[16], 2 * DFF, 1024, 0, 2 * DFF, q_Wgu_t, 0, DFF, scr, r, lane); continue; } r -= I_GU;
.LBB0_21:
	s_andn2_b64 vcc, exec, s[18:19]
	s_cbranch_vccnz .LBB0_23
; #define LAS __attribute__((address_space(3)))
; #define in KArgIn()
; __device__ __forceinline__ void tr_block8(const float* src, int ldw, unsigned char* dst  , int Kb, float sc, LAS float* scr, int lane) {
;     const int kr = lane >> 3, c4 = lane & 7;
;     f32x4 v[8];
; #pragma unroll
;     for (int i = 0; i < 8; ++i) v[i] = *(const f32x4*)(src + (size_t)(8 * i + kr) * ldw + 4 * c4);
; #pragma unroll
;     for (int i = 0; i < 8; ++i) { LAS float* d = scr + (8 * i + kr) * 33 + 4 * c4; d[0] = v[i].x; d[1] = v[i].y; d[2] = v[i].z; d[3] = v[i].w; }
;     asm volatile("s_waitcnt lgkmcnt(0)" ::: "memory");
;     const int c = lane & 7;
; #pragma unroll
;     for (int j = 0; j < 4; ++j) { const int n = (lane >> 3) + 8 * j; const LAS float* s = scr + (8 * c) * 33 + n;
;         int w0 = 0, w1 = 0; w0 = __builtin_amdgcn_cvt_pk_fp8_f32(s[0 * 33] * sc, s[1 * 33] * sc, w0, false); w0 = __builtin_amdgcn_cvt_pk_fp8_f32(s[2 * 33] * sc, s[3 * 33] * sc, w0, true);
;         w1 = __builtin_amdgcn_cvt_pk_fp8_f32(s[4 * 33] * sc, s[5 * 33] * sc, w1, false); w1 = __builtin_amdgcn_cvt_pk_fp8_f32(s[6 * 33] * sc, s[7 * 33] * sc, w1, true);
;         *(v2u*)(dst + (size_t)n * Kb + 8 * c) = (v2u){(unsigned)w0, (unsigned)w1}; }
;     asm volatile("s_waitcnt lgkmcnt(0)" ::: "memory");
; }
; template <int MAP> __device__ __forceinline__ void tr_seg8(const float* W, int ldw, int K, int c0, int ncols, unsigned char* WT, int row_off, int F, float sc, LAS float* scr, int item, int lane) {
;     const int nblk = ncols / 32, kb = item / nblk, nb = item % nblk, k0 = 64 * kb, n0 = 32 * nb;
;     int drow;
;     if (MAP == 0) drow = row_off + n0; else { int c = n0; const int up = c >= F; if (up) c -= F; drow = row_off + 256 * (c / 128) + 128 * up + (c % 128); }
;     tr_block8(W + (size_t)k0 * ldw + c0 + n0, ldw, WT + (size_t)drow * K + k0, K, sc, scr, lane);
; }
; template <int SEL> __global__ void __launch_bounds__(NWAVES * 64, 2) fwd_kernel(Args args) {
;     ...
;             if (r < I_GU) { if constexpr (DENSE_FP8 != 0) tr_seg8<1>(in[16], 2 * DFF, 1024, 0, 2 * DFF, (unsigned char*)q_Wgu_t, 0, DFF, W8_SCALE, scr, r, lane); else tr_seg<1>(in[16], 2 * DFF, 1024, 0, 2 * DFF, q_Wgu_t, 0, DFF, scr, r, lane); continue; } r -= I_GU;
	s_add_i32 s20, s4, 0xe400
	s_and_b32 s21, s20, 0xffff
	s_mul_i32 s21, s21, 0xba2f
	s_lshr_b32 s21, s21, 23
	s_mul_i32 s54, s21, 0xb0
	s_sub_i32 s54, s20, s54
	s_lshl_b32 s20, s54, 5
	s_and_b32 s55, s54, 0xffff
	s_cmpk_lt_u32 s55, 0x58
	s_cselect_b32 s56, 0, 0xfffff500
	s_cselect_b32 s55, 0, 0x80
	s_add_i32 s20, s56, s20
	s_sext_i32_i16 s57, s20
	s_bfe_u32 s57, s57, 0x70018
	s_mov_b64 s[18:19], s[0:1]
	s_add_i32 s57, s20, s57
	s_load_dwordx2 s[52:53], s[18:19], 0x80
	s_sext_i32_i16 s58, s57
	s_and_b32 s57, s57, 0xff80
	s_sub_i32 s20, s20, s57
	s_lshl_b32 s58, s58, 1
	s_sext_i32_i16 s20, s20
	s_and_b32 s58, s58, 0xffffff00
	s_add_i32 s20, s55, s20
	s_lshl_b32 s56, s21, 6
	s_add_i32 s20, s20, s58
	s_mul_i32 s21, s21, 0x160000
	s_waitcnt lgkmcnt(0)
	s_add_u32 s21, s52, s21
	s_addc_u32 s53, s53, 0
	s_lshl_b32 s52, s54, 7
	s_and_b32 s52, s52, 0x3ff80
	s_add_u32 s52, s21, s52
	s_addc_u32 s53, s53, 0
	v_lshl_add_u64 v[92:93], s[52:53], 0, v[2:3]
	v_mov_b32_e32 v51, v3
	v_lshl_add_u64 v[88:89], v[92:93], 0, v[50:51]
	v_add_co_u32_e32 v68, vcc, s42, v88
	v_mov_b32_e32 v55, v3
	s_nop 0
	v_addc_co_u32_e32 v69, vcc, 0, v89, vcc
	v_add_co_u32_e32 v80, vcc, s43, v88
	v_mov_b32_e32 v57, v3
	s_nop 0
	v_addc_co_u32_e32 v81, vcc, 0, v89, vcc
	v_add_co_u32_e32 v84, vcc, s44, v88
	s_mov_b64 s[18:19], s[0:1]
	s_nop 0
	v_addc_co_u32_e32 v85, vcc, 0, v89, vcc
	v_lshl_add_u64 v[72:73], v[92:93], 0, v[54:55]
	v_lshl_add_u64 v[76:77], v[92:93], 0, v[56:57]
	global_load_dwordx4 v[64:67], v[88:89], off nt
	s_nop 0
	global_load_dwordx4 v[68:71], v[68:69], off nt
	v_add_co_u32_e32 v88, vcc, s45, v88
	global_load_dwordx4 v[72:75], v[72:73], off nt
	s_nop 0
	global_load_dwordx4 v[76:79], v[76:77], off nt
	s_nop 0
	global_load_dwordx4 v[80:83], v[80:81], off nt
	s_nop 0
	global_load_dwordx4 v[84:87], v[84:85], off nt
	v_addc_co_u32_e32 v89, vcc, 0, v89, vcc
	global_load_dwordx4 v[88:91], v[88:89], off nt
	v_mov_b32_e32 v53, v3
	v_lshl_add_u64 v[92:93], v[92:93], 0, v[52:53]
	global_load_dwordx4 v[92:95], v[92:93], off nt
	v_add_u32_e32 v19, v13, v15
	v_add_u32_e32 v27, 0x420, v19
	v_add_u32_e32 v29, 0x428, v19
	v_add_u32_e32 v31, 0x840, v19
	v_add_u32_e32 v33, 0x848, v19
	v_add_u32_e32 v35, 0xc60, v19
	v_add_u32_e32 v37, 0xc68, v19
	v_add_u32_e32 v39, 0x1080, v19
	v_add_u32_e32 v41, 0x1088, v19
	v_add_u32_e32 v43, 0x14a0, v19
	v_add_u32_e32 v45, 0x14a8, v19
	v_add_u32_e32 v47, 0x18c0, v19
	v_add_u32_e32 v49, 0x18c8, v19
	s_load_dwordx2 s[18:19], s[18:19], 0xc0
	v_add_u32_e32 v51, 0x1ce0, v19
	v_add_u32_e32 v53, 0x1ce8, v19
	s_ashr_i32 s21, s20, 31
	s_lshl_b64 s[20:21], s[20:21], 10
	s_waitcnt lgkmcnt(0)
	s_add_u32 s18, s18, s20
	s_addc_u32 s19, s19, s21
	s_add_u32 s18, s18, s56
	s_addc_u32 s19, s19, 0
	s_waitcnt vmcnt(7)
	ds_write2_b32 v19, v64, v65 offset1:1
	ds_write2_b32 v19, v66, v67 offset0:2 offset1:3
	s_waitcnt vmcnt(5)
	ds_write2_b32 v47, v72, v73 offset1:1
	ds_write2_b32 v49, v74, v75 offset1:1
	s_waitcnt vmcnt(4)
	ds_write2_b32 v51, v76, v77 offset1:1
	ds_write2_b32 v53, v78, v79 offset1:1
	ds_write2_b32 v27, v68, v69 offset1:1
	ds_write2_b32 v29, v70, v71 offset1:1
	s_waitcnt vmcnt(3)
	ds_write2_b32 v31, v80, v81 offset1:1
	ds_write2_b32 v33, v82, v83 offset1:1
	s_waitcnt vmcnt(2)
	ds_write2_b32 v35, v84, v85 offset1:1
	ds_write2_b32 v37, v86, v87 offset1:1
	s_waitcnt vmcnt(1)
	ds_write2_b32 v39, v88, v89 offset1:1
	ds_write2_b32 v41, v90, v91 offset1:1
	s_waitcnt vmcnt(0)
	ds_write2_b32 v43, v92, v93 offset1:1
	ds_write2_b32 v45, v94, v95 offset1:1
	s_waitcnt lgkmcnt(0)
	ds_read2_b32 v[64:65], v17 offset1:8
	ds_read2_b32 v[66:67], v17 offset0:33 offset1:41
	ds_read2_b32 v[72:73], v17 offset0:66 offset1:74
	ds_read2_b32 v[74:75], v17 offset0:99 offset1:107
	ds_read2_b32 v[76:77], v17 offset0:132 offset1:140
	ds_read2_b32 v[78:79], v17 offset0:165 offset1:173
	v_mov_b32_e32 v70, v3
	ds_read2_b32 v[80:81], v17 offset0:198 offset1:206
	ds_read2_b32 v[82:83], v17 offset0:231 offset1:239
	s_waitcnt lgkmcnt(7)
	v_mul_f32_e32 v19, 0x42800000, v64
	s_waitcnt lgkmcnt(6)
	v_mul_f32_e32 v27, 0x42800000, v66
	v_cvt_pk_fp8_f32 v70, v19, v27
	s_waitcnt lgkmcnt(3)
	v_mul_f32_e32 v29, 0x42800000, v76
	s_waitcnt lgkmcnt(2)
	v_mul_f32_e32 v31, 0x42800000, v78
	v_mov_b32_e32 v71, v3
	v_cvt_pk_fp8_f32 v71, v29, v31
	v_mul_f32_e32 v19, 0x42800000, v72
	v_mul_f32_e32 v27, 0x42800000, v74
	v_cvt_pk_fp8_f32 v70, v19, v27 op_sel:[0,0,1]
	s_waitcnt lgkmcnt(1)
	v_mul_f32_e32 v19, 0x42800000, v80
	s_waitcnt lgkmcnt(0)
	v_mul_f32_e32 v27, 0x42800000, v82
	v_cvt_pk_fp8_f32 v71, v19, v27 op_sel:[0,0,1]
	v_mul_f32_e32 v19, 0x42800000, v65
	v_mul_f32_e32 v27, 0x42800000, v67
	v_mov_b32_e32 v64, v3
	v_cvt_pk_fp8_f32 v64, v19, v27
	v_mul_f32_e32 v29, 0x42800000, v77
	v_mul_f32_e32 v31, 0x42800000, v79
	v_mov_b32_e32 v65, v3
	v_cvt_pk_fp8_f32 v65, v29, v31
	v_mul_f32_e32 v19, 0x42800000, v73
	v_mul_f32_e32 v27, 0x42800000, v75
	v_cvt_pk_fp8_f32 v64, v19, v27 op_sel:[0,0,1]
	v_mul_f32_e32 v19, 0x42800000, v81
	v_mul_f32_e32 v27, 0x42800000, v83
	v_lshl_add_u64 v[68:69], s[18:19], 0, v[20:21]
	v_cvt_pk_fp8_f32 v65, v19, v27 op_sel:[0,0,1]
	v_lshl_add_u64 v[68:69], v[68:69], 0, s[8:9]
	v_lshl_add_u64 v[84:85], v[68:69], 0, v[4:5]
	ds_read2_b32 v[66:67], v17 offset0:16 offset1:24
	ds_read2_b32 v[72:73], v17 offset0:49 offset1:57
	global_store_dwordx2 v[84:85], v[70:71], off
	v_lshl_add_u64 v[70:71], v[68:69], 0, v[6:7]
	global_store_dwordx2 v[70:71], v[64:65], off
	ds_read2_b32 v[70:71], v17 offset0:82 offset1:90
	ds_read2_b32 v[74:75], v17 offset0:115 offset1:123
	ds_read2_b32 v[76:77], v17 offset0:148 offset1:156
	ds_read2_b32 v[78:79], v17 offset0:181 offset1:189
	s_waitcnt lgkmcnt(5)
	v_mul_f32_e32 v19, 0x42800000, v66
	s_waitcnt lgkmcnt(4)
	v_mul_f32_e32 v27, 0x42800000, v72
	v_mov_b32_e32 v64, v3
	ds_read2_b32 v[80:81], v17 offset0:214 offset1:222
	ds_read2_b32 v[82:83], v17 offset0:247 offset1:255
	v_cvt_pk_fp8_f32 v64, v19, v27
	s_waitcnt lgkmcnt(3)
	v_mul_f32_e32 v29, 0x42800000, v76
	s_waitcnt lgkmcnt(2)
	v_mul_f32_e32 v31, 0x42800000, v78
	v_mov_b32_e32 v65, v3
	v_cvt_pk_fp8_f32 v65, v29, v31
	v_mul_f32_e32 v19, 0x42800000, v70
	v_mul_f32_e32 v27, 0x42800000, v74
	v_cvt_pk_fp8_f32 v64, v19, v27 op_sel:[0,0,1]
	s_waitcnt lgkmcnt(1)
	v_mul_f32_e32 v19, 0x42800000, v80
	s_waitcnt lgkmcnt(0)
	v_mul_f32_e32 v27, 0x42800000, v82
	v_cvt_pk_fp8_f32 v65, v19, v27 op_sel:[0,0,1]
	v_mul_f32_e32 v19, 0x42800000, v67
	v_mul_f32_e32 v27, 0x42800000, v73
	v_mov_b32_e32 v66, v3
	v_cvt_pk_fp8_f32 v66, v19, v27
	v_mul_f32_e32 v29, 0x42800000, v77
	v_mul_f32_e32 v31, 0x42800000, v79
	v_mov_b32_e32 v67, v3
	v_cvt_pk_fp8_f32 v67, v29, v31
	v_mul_f32_e32 v19, 0x42800000, v71
	v_mul_f32_e32 v27, 0x42800000, v75
	v_cvt_pk_fp8_f32 v66, v19, v27 op_sel:[0,0,1]
	v_mul_f32_e32 v19, 0x42800000, v81
	v_mul_f32_e32 v27, 0x42800000, v83
	v_cvt_pk_fp8_f32 v67, v19, v27 op_sel:[0,0,1]
	v_lshl_add_u64 v[70:71], v[68:69], 0, v[8:9]
	global_store_dwordx2 v[70:71], v[64:65], off
	v_lshl_add_u64 v[64:65], v[68:69], 0, v[10:11]
	global_store_dwordx2 v[64:65], v[66:67], off
	s_waitcnt lgkmcnt(0)

; #define LAS __attribute__((address_space(3)))
; #define in KArgIn()
; __device__ __forceinline__ void tr_block(const float* src  , int ldw, bf16* dst  , int K, LAS float* scr, int lane) {
;     const int kr = lane >> 3, c4 = lane & 7;
;     f32x4 v[8];
; #pragma unroll
;     for (int i = 0; i < 8; ++i) v[i] = *(const f32x4*)(src + (size_t)(8 * i + kr) * ldw + 4 * c4);
; #pragma unroll
;     for (int i = 0; i < 8; ++i) { LAS float* d = scr + (8 * i + kr) * 33 + 4 * c4; d[0] = v[i].x; d[1] = v[i].y; d[2] = v[i].z; d[3] = v[i].w; }
;     asm volatile("s_waitcnt lgkmcnt(0)" ::: "memory");
; template <int SEL> __global__ void __launch_bounds__(NWAVES * 64, 2) fwd_kernel(Args args) {
;     ...
;             if (r < 2 * I_L) { const int l = r / I_L; r -= l * I_L; const float* win = in[3] + (size_t)l * 1024 * NIN; bf16* wt = q_Win_t + (size_t)l * NPROJ * 1024;
;                 if (r < I_A) { tr_seg<0>(win, NIN, 1024, 0, 1536, wt, 0, 0, scr, r, lane); continue; } r -= I_A;
;                 if (r < I_B) { tr_seg<0>(win, NIN, 1024, 1544, 3584, wt, 1536, 0, scr, r, lane); continue; } r -= I_B;
;                 if (r < I_BR) { tr_seg<0>(in[10] + (size_t)l * 512 * 1024, 1024, 512, 0, 1024, q_Wbr_t + (size_t)l * 2048 * 512, 0, 0, scr, r, lane); continue; } r -= I_BR;
;                 if (r < I_BR) { tr_seg<0>(in[11] + (size_t)l * 512 * 1024, 1024, 512, 0, 1024, q_Wbr_t + (size_t)l * 2048 * 512, 1024, 0, scr, r, lane); continue; } r -= I_BR;
;                 tr_seg<0>(in[12] + (size_t)l * 1024 * 1024, 1024, 1024, 0, 1024, q_Wo_t + (size_t)l * 1024 * 1024, 0, 0, scr, r, lane); continue; }
.LBB0_24:
	s_andn2_b64 vcc, exec, s[18:19]
	s_cbranch_vccnz .LBB0_9
	s_mul_hi_i32 s18, s4, 0x92492493
	s_mov_b64 s[20:21], s[0:1]
	s_add_i32 s18, s18, s4
	s_lshr_b32 s4, s18, 31
	s_ashr_i32 s18, s18, 11
	s_load_dwordx2 s[20:21], s[20:21], 0x18
	s_mov_b64 s[52:53], s[0:1]
	s_add_i32 s18, s18, s4
	s_mul_i32 s4, s18, 0xfffff200
	s_load_dwordx2 s[52:53], s[52:53], 0xc0
	s_add_i32 s54, s3, s4
	s_add_i32 s54, s54, 0x9c80
	s_mul_i32 s19, s18, 0x1408000
	s_mul_hi_i32 s4, s18, 0x1408000
	s_waitcnt lgkmcnt(0)
	s_add_u32 s55, s20, s19
	s_addc_u32 s56, s21, s4
	s_mul_i32 s19, s18, 0xa00000
	s_mul_hi_i32 s4, s18, 0xa00000
	s_add_u32 s19, s52, s19
	s_addc_u32 s4, s53, s4
	s_add_u32 s52, s19, 0x1000000
	s_addc_u32 s53, s4, 0
	s_cmpk_gt_i32 s54, 0x2ff
	s_mov_b64 s[20:21], -1
	s_cbranch_scc0 .LBB0_39
	s_cmpk_gt_u32 s54, 0x9ff
	s_cbranch_scc0 .LBB0_36
	s_ashr_i32 s19, s18, 31
	s_cmpk_gt_u32 s54, 0xaff
	s_cbranch_scc0 .LBB0_33
	s_cmpk_gt_u32 s54, 0xbff
	s_cbranch_scc0 .LBB0_30
	s_mov_b64 s[20:21], s[0:1]
	s_load_dwordx2 s[20:21], s[20:21], 0x60
	s_mov_b64 s[58:59], s[0:1]
	s_load_dwordx2 s[58:59], s[58:59], 0xc0
	s_lshl_b64 s[60:61], s[18:19], 22
	s_waitcnt lgkmcnt(0)
	s_add_u32 s57, s20, s60
	s_addc_u32 s60, s21, s61
	s_lshl_b64 s[20:21], s[18:19], 21
	s_add_u32 s58, s58, s20
	s_mul_i32 s4, s18, 0xffffe400
	s_addc_u32 s59, s59, s21
	s_add_i32 s4, s23, s4
	s_andn2_b32 s4, s4, 63
	s_addk_i32 s4, 0xe800
	s_and_b32 s61, s27, 0x3e0
	s_lshl_b64 s[20:21], s[4:5], 12
	s_add_u32 s20, s57, s20
	s_addc_u32 s21, s60, s21
	s_lshl_b32 s57, s61, 2
	s_add_u32 s20, s20, s57
	s_addc_u32 s21, s21, 0
	v_lshl_add_u64 v[92:93], s[20:21], 0, v[2:3]
	v_mov_b32_e32 v59, v3
	v_mov_b32_e32 v61, v3
	v_mov_b32_e32 v63, v3
	v_lshlrev_b32_e32 v74, 2, v10
	v_mov_b32_e32 v75, v3
	v_lshlrev_b32_e32 v80, 2, v12
	v_mov_b32_e32 v81, v3
	v_lshlrev_b32_e32 v82, 2, v14
	v_mov_b32_e32 v83, v3
	v_lshl_add_u64 v[64:65], v[92:93], 0, v[58:59]
	v_lshl_add_u64 v[68:69], v[92:93], 0, v[60:61]
	v_lshl_add_u64 v[72:73], v[92:93], 0, v[62:63]
	v_lshl_add_u64 v[76:77], v[92:93], 0, v[74:75]
	v_lshl_add_u64 v[80:81], v[92:93], 0, v[80:81]
	v_lshl_add_u64 v[84:85], v[92:93], 0, v[82:83]
	global_load_dwordx4 v[64:67], v[64:65], off nt
	s_nop 0
	global_load_dwordx4 v[68:71], v[68:69], off nt
	s_nop 0
	global_load_dwordx4 v[72:75], v[72:73], off nt
	s_nop 0
	global_load_dwordx4 v[76:79], v[76:77], off nt
	s_nop 0
	global_load_dwordx4 v[80:83], v[80:81], off nt
	s_nop 0
	global_load_dwordx4 v[84:87], v[84:85], off nt
	v_lshlrev_b32_e32 v88, 2, v16
	v_mov_b32_e32 v89, v3
	v_lshl_add_u64 v[88:89], v[92:93], 0, v[88:89]
	global_load_dwordx4 v[88:91], v[88:89], off nt
	v_lshlrev_b32_e32 v94, 2, v18
	v_mov_b32_e32 v95, v3
	v_lshl_add_u64 v[92:93], v[92:93], 0, v[94:95]
	global_load_dwordx4 v[92:95], v[92:93], off nt
	v_add_u32_e32 v19, v13, v15
	v_add_u32_e32 v27, 0x420, v19
	v_add_u32_e32 v29, 0x428, v19
	v_add_u32_e32 v31, 0x840, v19
	v_add_u32_e32 v33, 0x848, v19
	v_add_u32_e32 v35, 0xc60, v19
	v_add_u32_e32 v37, 0xc68, v19
	v_add_u32_e32 v39, 0x1080, v19
	v_add_u32_e32 v41, 0x1088, v19
	v_add_u32_e32 v43, 0x14a0, v19
	v_add_u32_e32 v45, 0x14a8, v19
	v_add_u32_e32 v47, 0x18c0, v19
	v_add_u32_e32 v49, 0x18c8, v19
	v_add_u32_e32 v51, 0x1ce0, v19
	v_add_u32_e32 v53, 0x1ce8, v19
	s_lshl_b32 s20, s61, 11
	s_add_u32 s57, s58, s20
	s_addc_u32 s58, s59, 0
	s_lshl_b64 s[20:21], s[4:5], 1
	s_add_u32 s20, s57, s20
	v_lshlrev_b32_e32 v96, 1, v20
	v_mov_b32_e32 v97, v3
	s_addc_u32 s21, s58, s21
	v_lshl_add_u64 v[96:97], s[20:21], 0, v[96:97]
	v_lshl_add_u64 v[96:97], v[96:97], 0, s[10:11]
	s_mov_b64 s[20:21], 0
	s_waitcnt vmcnt(7)
	ds_write2_b32 v19, v64, v65 offset1:1
	ds_write2_b32 v19, v66, v67 offset0:2 offset1:3
	s_waitcnt vmcnt(6)
	ds_write2_b32 v27, v68, v69 offset1:1
	ds_write2_b32 v29, v70, v71 offset1:1
	s_waitcnt vmcnt(5)
	ds_write2_b32 v31, v72, v73 offset1:1
	ds_write2_b32 v33, v74, v75 offset1:1
	s_waitcnt vmcnt(4)
	ds_write2_b32 v35, v76, v77 offset1:1
	ds_write2_b32 v37, v78, v79 offset1:1
	s_waitcnt vmcnt(3)
	ds_write2_b32 v39, v80, v81 offset1:1
	ds_write2_b32 v41, v82, v83 offset1:1
	s_waitcnt vmcnt(2)
	ds_write2_b32 v43, v84, v85 offset1:1
	ds_write2_b32 v45, v86, v87 offset1:1
	s_waitcnt vmcnt(1)
	ds_write2_b32 v47, v88, v89 offset1:1
	ds_write2_b32 v49, v90, v91 offset1:1
	s_waitcnt vmcnt(0)
	ds_write2_b32 v51, v92, v93 offset1:1
	ds_write2_b32 v53, v94, v95 offset1:1
	s_waitcnt lgkmcnt(0)
	ds_read2_b32 v[68:69], v17 offset1:8
	ds_read2_b32 v[70:71], v17 offset0:33 offset1:41
	ds_read2_b32 v[72:73], v17 offset0:66 offset1:74
	ds_read2_b32 v[74:75], v17 offset0:99 offset1:107
	ds_read2_b32 v[76:77], v17 offset0:132 offset1:140
	ds_read2_b32 v[78:79], v17 offset0:165 offset1:173
	s_waitcnt lgkmcnt(5)
	v_bfe_u32 v19, v68, 16, 1
	s_waitcnt lgkmcnt(4)
	v_bfe_u32 v27, v70, 16, 1
	v_add3_u32 v19, v68, v19, s46
	ds_read2_b32 v[80:81], v17 offset0:198 offset1:206
	v_add3_u32 v27, v70, v27, s46
	v_lshrrev_b32_e32 v19, 16, v19
	ds_read2_b32 v[82:83], v17 offset0:231 offset1:239
	v_and_or_b32 v64, v27, s47, v19
	s_waitcnt lgkmcnt(3)
	v_bfe_u32 v19, v76, 16, 1
	v_add3_u32 v19, v76, v19, s46
	s_waitcnt lgkmcnt(2)
	v_bfe_u32 v27, v78, 16, 1
	v_lshrrev_b32_e32 v19, 16, v19
	v_add3_u32 v27, v78, v27, s46
	v_and_or_b32 v66, v27, s47, v19
	s_waitcnt lgkmcnt(1)
	v_bfe_u32 v19, v80, 16, 1
	v_add3_u32 v19, v80, v19, s46
	s_waitcnt lgkmcnt(0)
; #define LAS __attribute__((address_space(3)))
; __device__ __forceinline__ unsigned pk2(float lo, float hi) { return f2bf(lo) | (f2bf(hi) << 16); }
; #define in KArgIn()
; __device__ __forceinline__ void tr_block(const float* src  , int ldw, bf16* dst  , int K, LAS float* scr, int lane) {
;     ...
; #pragma unroll
;     for (int i = 0; i < 8; ++i) { LAS float* d = scr + (8 * i + kr) * 33 + 4 * c4; d[0] = v[i].x; d[1] = v[i].y; d[2] = v[i].z; d[3] = v[i].w; }
;     asm volatile("s_waitcnt lgkmcnt(0)" ::: "memory");
;     const int c = lane & 7;
; #pragma unroll
;     for (int j = 0; j < 4; ++j) { const int n = (lane >> 3) + 8 * j; const LAS float* s = scr + (8 * c) * 33 + n;
;         v4u o; o.x = pk2(s[0 * 33], s[1 * 33]); o.y = pk2(s[2 * 33], s[3 * 33]); o.z = pk2(s[4 * 33], s[5 * 33]); o.w = pk2(s[6 * 33], s[7 * 33]);
;         *(v4u*)(dst + (size_t)n * K + 8 * c) = o; }
;     asm volatile("s_waitcnt lgkmcnt(0)" ::: "memory");
; }
; template <int SEL> __global__ void __launch_bounds__(NWAVES * 64, 2) fwd_kernel(Args args) {
;     ...
;                 if (r < I_BR) { tr_seg<0>(in[11] + (size_t)l * 512 * 1024, 1024, 512, 0, 1024, q_Wbr_t + (size_t)l * 2048 * 512, 1024, 0, scr, r, lane); continue; } r -= I_BR;
	v_bfe_u32 v27, v82, 16, 1
	v_bfe_u32 v29, v72, 16, 1
	v_lshrrev_b32_e32 v19, 16, v19
	v_add3_u32 v27, v82, v27, s46
	v_bfe_u32 v31, v74, 16, 1
	v_add3_u32 v29, v72, v29, s46
	v_and_or_b32 v67, v27, s47, v19
	v_bfe_u32 v19, v69, 16, 1
	v_add3_u32 v31, v74, v31, s46
	v_lshrrev_b32_e32 v29, 16, v29
	v_lshlrev_b32_e32 v84, 1, v4
	v_mov_b32_e32 v85, v3
	v_add3_u32 v19, v69, v19, s46
	v_bfe_u32 v27, v71, 16, 1
	v_and_or_b32 v65, v31, s47, v29
	v_lshl_add_u64 v[84:85], v[96:97], 0, v[84:85]
	v_lshrrev_b32_e32 v19, 16, v19
	v_add3_u32 v27, v71, v27, s46
	global_store_dwordx4 v[84:85], v[64:67], off
	v_lshlrev_b32_e32 v68, 1, v6
	v_mov_b32_e32 v69, v3
	v_and_or_b32 v64, v27, s47, v19
	v_bfe_u32 v19, v73, 16, 1
	v_add3_u32 v19, v73, v19, s46
	v_bfe_u32 v27, v75, 16, 1
	v_lshrrev_b32_e32 v19, 16, v19
	v_add3_u32 v27, v75, v27, s46
	v_and_or_b32 v65, v27, s47, v19
	v_bfe_u32 v19, v77, 16, 1
	v_add3_u32 v19, v77, v19, s46
	v_bfe_u32 v27, v79, 16, 1
	v_lshrrev_b32_e32 v19, 16, v19
	v_add3_u32 v27, v79, v27, s46
	v_and_or_b32 v66, v27, s47, v19
	v_bfe_u32 v19, v81, 16, 1
	v_add3_u32 v19, v81, v19, s46
	v_bfe_u32 v27, v83, 16, 1
	v_lshrrev_b32_e32 v19, 16, v19
	v_add3_u32 v27, v83, v27, s46
	v_and_or_b32 v67, v27, s47, v19
	ds_read2_b32 v[70:71], v17 offset0:16 offset1:24
	v_lshl_add_u64 v[68:69], v[96:97], 0, v[68:69]
	global_store_dwordx4 v[68:69], v[64:67], off
	ds_read2_b32 v[68:69], v17 offset0:49 offset1:57
	ds_read2_b32 v[72:73], v17 offset0:82 offset1:90
	ds_read2_b32 v[74:75], v17 offset0:115 offset1:123
	s_waitcnt lgkmcnt(3)
	v_bfe_u32 v19, v70, 16, 1
	v_add3_u32 v19, v70, v19, s46
	s_waitcnt lgkmcnt(2)
	v_bfe_u32 v27, v68, 16, 1
	ds_read2_b32 v[76:77], v17 offset0:148 offset1:156
	v_lshrrev_b32_e32 v19, 16, v19
	v_add3_u32 v27, v68, v27, s46
	ds_read2_b32 v[78:79], v17 offset0:181 offset1:189
	v_and_or_b32 v64, v27, s47, v19
	s_waitcnt lgkmcnt(3)
	v_bfe_u32 v19, v72, 16, 1
	v_add3_u32 v19, v72, v19, s46
	s_waitcnt lgkmcnt(2)
	v_bfe_u32 v27, v74, 16, 1
	ds_read2_b32 v[80:81], v17 offset0:214 offset1:222
	v_lshrrev_b32_e32 v19, 16, v19
	v_add3_u32 v27, v74, v27, s46
	ds_read2_b32 v[82:83], v17 offset0:247 offset1:255
	v_and_or_b32 v65, v27, s47, v19
	s_waitcnt lgkmcnt(3)
	v_bfe_u32 v19, v76, 16, 1
	v_add3_u32 v19, v76, v19, s46
	s_waitcnt lgkmcnt(2)
	v_bfe_u32 v27, v78, 16, 1
	v_lshrrev_b32_e32 v19, 16, v19
	v_add3_u32 v27, v78, v27, s46
	v_and_or_b32 v66, v27, s47, v19
	s_waitcnt lgkmcnt(1)
	v_bfe_u32 v19, v80, 16, 1
	v_add3_u32 v19, v80, v19, s46
	s_waitcnt lgkmcnt(0)
	v_bfe_u32 v27, v82, 16, 1
	v_lshrrev_b32_e32 v19, 16, v19
	v_add3_u32 v27, v82, v27, s46
	v_and_or_b32 v67, v27, s47, v19
	v_bfe_u32 v19, v71, 16, 1
	v_lshlrev_b32_e32 v84, 1, v8
	v_mov_b32_e32 v85, v3
	v_add3_u32 v19, v71, v19, s46
	v_bfe_u32 v27, v69, 16, 1
	v_lshl_add_u64 v[84:85], v[96:97], 0, v[84:85]
	v_lshrrev_b32_e32 v19, 16, v19
	v_add3_u32 v27, v69, v27, s46
	global_store_dwordx4 v[84:85], v[64:67], off
	v_lshlrev_b32_e32 v68, 1, v10
	v_mov_b32_e32 v69, v3
	v_and_or_b32 v64, v27, s47, v19
	v_bfe_u32 v19, v73, 16, 1
	v_add3_u32 v19, v73, v19, s46
	v_bfe_u32 v27, v75, 16, 1
	v_lshrrev_b32_e32 v19, 16, v19
	v_add3_u32 v27, v75, v27, s46
	v_and_or_b32 v65, v27, s47, v19
	v_bfe_u32 v19, v77, 16, 1
	v_add3_u32 v19, v77, v19, s46
	v_bfe_u32 v27, v79, 16, 1
	v_lshrrev_b32_e32 v19, 16, v19
	v_add3_u32 v27, v79, v27, s46
	v_and_or_b32 v66, v27, s47, v19
	v_bfe_u32 v19, v81, 16, 1
	v_add3_u32 v19, v81, v19, s46
	v_bfe_u32 v27, v83, 16, 1
	v_lshrrev_b32_e32 v19, 16, v19
	v_add3_u32 v27, v83, v27, s46
	v_and_or_b32 v67, v27, s47, v19
	v_lshl_add_u64 v[68:69], v[96:97], 0, v[68:69]
	global_store_dwordx4 v[68:69], v[64:67], off
	s_waitcnt lgkmcnt(0)
.LBB0_30:
	s_andn2_b64 vcc, exec, s[20:21]
	s_cbranch_vccnz .LBB0_32
	s_mov_b64 s[20:21], s[0:1]
	s_load_dwordx2 s[20:21], s[20:21], 0x58
	s_mov_b64 s[58:59], s[0:1]
	s_load_dwordx2 s[58:59], s[58:59], 0xc0
	s_lshl_b64 s[60:61], s[18:19], 21
	s_waitcnt lgkmcnt(0)
	s_add_u32 s4, s20, s60
	s_addc_u32 s20, s21, s61
	v_mov_b32_e32 v59, v3
	s_add_u32 s57, s58, s60
	s_addc_u32 s58, s59, s61
	s_and_b32 s59, s23, 0x1c0
	s_and_b32 s60, s27, 0x3e0
	s_lshl_b32 s21, s59, 12
	s_add_u32 s4, s4, s21
	s_addc_u32 s21, s20, 0
	s_lshl_b32 s20, s60, 2
	s_add_u32 s20, s4, s20
	s_addc_u32 s21, s21, 0
	v_lshl_add_u64 v[92:93], s[20:21], 0, v[2:3]
	v_mov_b32_e32 v61, v3
	v_mov_b32_e32 v63, v3
	v_lshlrev_b32_e32 v74, 2, v10
	v_mov_b32_e32 v75, v3
	v_lshlrev_b32_e32 v80, 2, v12
	v_mov_b32_e32 v81, v3
	v_lshlrev_b32_e32 v82, 2, v14
	v_mov_b32_e32 v83, v3
	v_lshl_add_u64 v[64:65], v[92:93], 0, v[58:59]
	v_lshl_add_u64 v[68:69], v[92:93], 0, v[60:61]
	v_lshl_add_u64 v[72:73], v[92:93], 0, v[62:63]
	v_lshl_add_u64 v[76:77], v[92:93], 0, v[74:75]
	v_lshl_add_u64 v[80:81], v[92:93], 0, v[80:81]
	v_lshl_add_u64 v[84:85], v[92:93], 0, v[82:83]
	global_load_dwordx4 v[64:67], v[64:65], off nt
	s_nop 0
	global_load_dwordx4 v[68:71], v[68:69], off nt
	s_nop 0
	global_load_dwordx4 v[72:75], v[72:73], off nt
	s_nop 0
	global_load_dwordx4 v[76:79], v[76:77], off nt
	s_nop 0
	global_load_dwordx4 v[80:83], v[80:81], off nt
	s_nop 0
	global_load_dwordx4 v[84:87], v[84:85], off nt
	v_lshlrev_b32_e32 v88, 2, v16
	v_mov_b32_e32 v89, v3
	v_lshl_add_u64 v[88:89], v[92:93], 0, v[88:89]
	global_load_dwordx4 v[88:91], v[88:89], off nt
	v_lshlrev_b32_e32 v94, 2, v18
	v_mov_b32_e32 v95, v3
	v_lshl_add_u64 v[92:93], v[92:93], 0, v[94:95]
	global_load_dwordx4 v[92:95], v[92:93], off nt
	v_add_u32_e32 v19, v13, v15
	v_add_u32_e32 v27, 0x420, v19
	v_add_u32_e32 v29, 0x428, v19
	v_add_u32_e32 v31, 0x840, v19
	v_add_u32_e32 v33, 0x848, v19
	v_add_u32_e32 v35, 0xc60, v19
	v_add_u32_e32 v37, 0xc68, v19
	v_add_u32_e32 v39, 0x1080, v19
	v_add_u32_e32 v41, 0x1088, v19
	v_add_u32_e32 v43, 0x14a0, v19
	v_add_u32_e32 v45, 0x14a8, v19
	v_add_u32_e32 v47, 0x18c0, v19
	v_add_u32_e32 v49, 0x18c8, v19
	v_add_u32_e32 v51, 0x1ce0, v19
	v_add_u32_e32 v53, 0x1ce8, v19
	s_lshl_b32 s4, s60, 10
	s_add_u32 s4, s57, s4
	s_addc_u32 s21, s58, 0
	s_lshl_b32 s20, s59, 1
	s_add_u32 s20, s4, s20
	v_lshlrev_b32_e32 v96, 1, v20
	v_mov_b32_e32 v97, v3
	s_addc_u32 s21, s21, 0
	v_lshl_add_u64 v[96:97], s[20:21], 0, v[96:97]
	v_lshl_add_u64 v[96:97], v[96:97], 0, s[12:13]
	s_waitcnt vmcnt(7)
; #define LAS __attribute__((address_space(3)))
; __device__ __forceinline__ unsigned pk2(float lo, float hi) { return f2bf(lo) | (f2bf(hi) << 16); }
; __device__ __forceinline__ void tr_block(const float* src  , int ldw, bf16* dst  , int K, LAS float* scr, int lane) {
;     ...
; #pragma unroll
;     for (int i = 0; i < 8; ++i) { LAS float* d = scr + (8 * i + kr) * 33 + 4 * c4; d[0] = v[i].x; d[1] = v[i].y; d[2] = v[i].z; d[3] = v[i].w; }
;     asm volatile("s_waitcnt lgkmcnt(0)" ::: "memory");
;     const int c = lane & 7;
; #pragma unroll
;     for (int j = 0; j < 4; ++j) { const int n = (lane >> 3) + 8 * j; const LAS float* s = scr + (8 * c) * 33 + n;
;         v4u o; o.x = pk2(s[0 * 33], s[1 * 33]); o.y = pk2(s[2 * 33], s[3 * 33]); o.z = pk2(s[4 * 33], s[5 * 33]); o.w = pk2(s[6 * 33], s[7 * 33]);
;         *(v4u*)(dst + (size_t)n * K + 8 * c) = o; }
;     asm volatile("s_waitcnt lgkmcnt(0)" ::: "memory");
	ds_write2_b32 v19, v64, v65 offset1:1
	ds_write2_b32 v19, v66, v67 offset0:2 offset1:3
	s_waitcnt vmcnt(6)
	ds_write2_b32 v27, v68, v69 offset1:1
	ds_write2_b32 v29, v70, v71 offset1:1
	s_waitcnt vmcnt(5)
	ds_write2_b32 v31, v72, v73 offset1:1
	ds_write2_b32 v33, v74, v75 offset1:1
	s_waitcnt vmcnt(4)
	ds_write2_b32 v35, v76, v77 offset1:1
	ds_write2_b32 v37, v78, v79 offset1:1
	s_waitcnt vmcnt(3)
	ds_write2_b32 v39, v80, v81 offset1:1
	ds_write2_b32 v41, v82, v83 offset1:1
	s_waitcnt vmcnt(2)
	ds_write2_b32 v43, v84, v85 offset1:1
	ds_write2_b32 v45, v86, v87 offset1:1
	s_waitcnt vmcnt(1)
	ds_write2_b32 v47, v88, v89 offset1:1
	ds_write2_b32 v49, v90, v91 offset1:1
	s_waitcnt vmcnt(0)
	ds_write2_b32 v51, v92, v93 offset1:1
	ds_write2_b32 v53, v94, v95 offset1:1
	s_waitcnt lgkmcnt(0)
	ds_read2_b32 v[68:69], v17 offset0:33 offset1:41
	ds_read2_b32 v[70:71], v17 offset1:8
	ds_read2_b32 v[72:73], v17 offset0:66 offset1:74
	ds_read2_b32 v[74:75], v17 offset0:99 offset1:107
	ds_read2_b32 v[76:77], v17 offset0:132 offset1:140
	ds_read2_b32 v[78:79], v17 offset0:165 offset1:173
	s_waitcnt lgkmcnt(4)
	v_bfe_u32 v19, v70, 16, 1
	v_bfe_u32 v27, v68, 16, 1
	v_add3_u32 v19, v70, v19, s46
	ds_read2_b32 v[80:81], v17 offset0:198 offset1:206
	v_add3_u32 v27, v68, v27, s46
	v_lshrrev_b32_e32 v19, 16, v19
	ds_read2_b32 v[82:83], v17 offset0:231 offset1:239
	v_and_or_b32 v64, v27, s47, v19
	s_waitcnt lgkmcnt(3)
	v_bfe_u32 v19, v76, 16, 1
	v_add3_u32 v19, v76, v19, s46
	s_waitcnt lgkmcnt(2)
	v_bfe_u32 v27, v78, 16, 1
	v_lshrrev_b32_e32 v19, 16, v19
	v_add3_u32 v27, v78, v27, s46
	v_and_or_b32 v66, v27, s47, v19
	s_waitcnt lgkmcnt(1)
	v_bfe_u32 v19, v80, 16, 1
	v_add3_u32 v19, v80, v19, s46
	s_waitcnt lgkmcnt(0)
	v_bfe_u32 v27, v82, 16, 1
	v_bfe_u32 v29, v72, 16, 1
	v_lshrrev_b32_e32 v19, 16, v19
	v_add3_u32 v27, v82, v27, s46
	v_bfe_u32 v31, v74, 16, 1
	v_add3_u32 v29, v72, v29, s46
	v_and_or_b32 v67, v27, s47, v19
	v_bfe_u32 v19, v71, 16, 1
	v_add3_u32 v31, v74, v31, s46
	v_lshrrev_b32_e32 v29, 16, v29
	v_lshlrev_b32_e32 v84, 1, v26
	v_mov_b32_e32 v85, v3
	v_add3_u32 v19, v71, v19, s46
	v_bfe_u32 v27, v69, 16, 1
	v_and_or_b32 v65, v31, s47, v29
	v_lshl_add_u64 v[84:85], v[96:97], 0, v[84:85]
	v_lshrrev_b32_e32 v19, 16, v19
	v_add3_u32 v27, v69, v27, s46
	global_store_dwordx4 v[84:85], v[64:67], off
	v_lshlrev_b32_e32 v68, 1, v28
	v_mov_b32_e32 v69, v3
	v_and_or_b32 v64, v27, s47, v19
	v_bfe_u32 v19, v73, 16, 1
	v_add3_u32 v19, v73, v19, s46
	v_bfe_u32 v27, v75, 16, 1
	v_lshrrev_b32_e32 v19, 16, v19
	v_add3_u32 v27, v75, v27, s46
	v_and_or_b32 v65, v27, s47, v19
	v_bfe_u32 v19, v77, 16, 1
	v_add3_u32 v19, v77, v19, s46
	v_bfe_u32 v27, v79, 16, 1
	v_lshrrev_b32_e32 v19, 16, v19
	v_add3_u32 v27, v79, v27, s46
	v_and_or_b32 v66, v27, s47, v19
	v_bfe_u32 v19, v81, 16, 1
	v_add3_u32 v19, v81, v19, s46
	v_bfe_u32 v27, v83, 16, 1
	v_lshrrev_b32_e32 v19, 16, v19
	v_add3_u32 v27, v83, v27, s46
	v_and_or_b32 v67, v27, s47, v19
	ds_read2_b32 v[70:71], v17 offset0:16 offset1:24
	v_lshl_add_u64 v[68:69], v[96:97], 0, v[68:69]
	global_store_dwordx4 v[68:69], v[64:67], off
	ds_read2_b32 v[68:69], v17 offset0:49 offset1:57
	ds_read2_b32 v[72:73], v17 offset0:82 offset1:90
	ds_read2_b32 v[74:75], v17 offset0:115 offset1:123
	s_waitcnt lgkmcnt(3)
	v_bfe_u32 v19, v70, 16, 1
	v_add3_u32 v19, v70, v19, s46
	s_waitcnt lgkmcnt(2)
	v_bfe_u32 v27, v68, 16, 1
	ds_read2_b32 v[76:77], v17 offset0:148 offset1:156
	v_lshrrev_b32_e32 v19, 16, v19
	v_add3_u32 v27, v68, v27, s46
	ds_read2_b32 v[78:79], v17 offset0:181 offset1:189
	v_and_or_b32 v64, v27, s47, v19
	s_waitcnt lgkmcnt(3)
	v_bfe_u32 v19, v72, 16, 1
	v_add3_u32 v19, v72, v19, s46
	s_waitcnt lgkmcnt(2)
	v_bfe_u32 v27, v74, 16, 1
	ds_read2_b32 v[80:81], v17 offset0:214 offset1:222
	v_lshrrev_b32_e32 v19, 16, v19
	v_add3_u32 v27, v74, v27, s46
	ds_read2_b32 v[82:83], v17 offset0:247 offset1:255
	v_and_or_b32 v65, v27, s47, v19
	s_waitcnt lgkmcnt(3)
	v_bfe_u32 v19, v76, 16, 1
	v_add3_u32 v19, v76, v19, s46
	s_waitcnt lgkmcnt(2)
	v_bfe_u32 v27, v78, 16, 1
	v_lshrrev_b32_e32 v19, 16, v19
	v_add3_u32 v27, v78, v27, s46
	v_and_or_b32 v66, v27, s47, v19
	s_waitcnt lgkmcnt(1)
	v_bfe_u32 v19, v80, 16, 1
	v_add3_u32 v19, v80, v19, s46
	s_waitcnt lgkmcnt(0)
	v_bfe_u32 v27, v82, 16, 1
	v_lshrrev_b32_e32 v19, 16, v19
	v_add3_u32 v27, v82, v27, s46
	v_and_or_b32 v67, v27, s47, v19
	v_bfe_u32 v19, v71, 16, 1
	v_lshlrev_b32_e32 v84, 1, v30
	v_mov_b32_e32 v85, v3
	v_add3_u32 v19, v71, v19, s46
	v_bfe_u32 v27, v69, 16, 1
	v_lshl_add_u64 v[84:85], v[96:97], 0, v[84:85]
	v_lshrrev_b32_e32 v19, 16, v19
	v_add3_u32 v27, v69, v27, s46
	global_store_dwordx4 v[84:85], v[64:67], off
	v_lshlrev_b32_e32 v68, 1, v32
	v_mov_b32_e32 v69, v3
	v_and_or_b32 v64, v27, s47, v19
	v_bfe_u32 v19, v73, 16, 1
	v_add3_u32 v19, v73, v19, s46
	v_bfe_u32 v27, v75, 16, 1
	v_lshrrev_b32_e32 v19, 16, v19
	v_add3_u32 v27, v75, v27, s46
	v_and_or_b32 v65, v27, s47, v19
	v_bfe_u32 v19, v77, 16, 1
	v_add3_u32 v19, v77, v19, s46
	v_bfe_u32 v27, v79, 16, 1
	v_lshrrev_b32_e32 v19, 16, v19
	v_add3_u32 v27, v79, v27, s46
	v_and_or_b32 v66, v27, s47, v19
	v_bfe_u32 v19, v81, 16, 1
	v_add3_u32 v19, v81, v19, s46
	v_bfe_u32 v27, v83, 16, 1
	v_lshrrev_b32_e32 v19, 16, v19
	v_add3_u32 v27, v83, v27, s46
	v_and_or_b32 v67, v27, s47, v19
	v_lshl_add_u64 v[68:69], v[96:97], 0, v[68:69]
	global_store_dwordx4 v[68:69], v[64:67], off
	s_waitcnt lgkmcnt(0)

; #define LAS __attribute__((address_space(3)))
; __device__ __forceinline__ unsigned pk2(float lo, float hi) { return f2bf(lo) | (f2bf(hi) << 16); }
; __device__ __forceinline__ void tr_block(const float* src  , int ldw, bf16* dst  , int K, LAS float* scr, int lane) {
;     const int kr = lane >> 3, c4 = lane & 7;
;     f32x4 v[8];
; #pragma unroll
;     for (int i = 0; i < 8; ++i) v[i] = *(const f32x4*)(src + (size_t)(8 * i + kr) * ldw + 4 * c4);
; #pragma unroll
;     for (int i = 0; i < 8; ++i) { LAS float* d = scr + (8 * i + kr) * 33 + 4 * c4; d[0] = v[i].x; d[1] = v[i].y; d[2] = v[i].z; d[3] = v[i].w; }
;     asm volatile("s_waitcnt lgkmcnt(0)" ::: "memory");
;     const int c = lane & 7;
; #pragma unroll
;     for (int j = 0; j < 4; ++j) { const int n = (lane >> 3) + 8 * j; const LAS float* s = scr + (8 * c) * 33 + n;
;         v4u o; o.x = pk2(s[0 * 33], s[1 * 33]); o.y = pk2(s[2 * 33], s[3 * 33]); o.z = pk2(s[4 * 33], s[5 * 33]); o.w = pk2(s[6 * 33], s[7 * 33]);
;         *(v4u*)(dst + (size_t)n * K + 8 * c) = o; }
;     asm volatile("s_waitcnt lgkmcnt(0)" ::: "memory");
; }
.LBB0_33:
	s_andn2_b64 vcc, exec, s[20:21]
	s_cbranch_vccnz .LBB0_35
	s_mov_b64 s[20:21], s[0:1]
	s_load_dwordx2 s[20:21], s[20:21], 0x50
	s_mov_b64 s[58:59], s[0:1]
	s_load_dwordx2 s[58:59], s[58:59], 0xc0
	s_lshl_b64 s[18:19], s[18:19], 21
	s_waitcnt lgkmcnt(0)
	s_add_u32 s4, s20, s18
	s_addc_u32 s20, s21, s19
	v_mov_b32_e32 v59, v3
	s_add_u32 s21, s58, s18
	s_addc_u32 s57, s59, s19
	s_and_b32 s58, s23, 0x1c0
	s_and_b32 s59, s27, 0x3e0
	s_lshl_b32 s18, s58, 12
	s_add_u32 s4, s4, s18
	s_addc_u32 s19, s20, 0
	s_lshl_b32 s18, s59, 2
	s_add_u32 s18, s4, s18
	s_addc_u32 s19, s19, 0
	v_lshl_add_u64 v[92:93], s[18:19], 0, v[2:3]
	v_mov_b32_e32 v61, v3
	v_mov_b32_e32 v63, v3
	v_lshlrev_b32_e32 v74, 2, v10
	v_mov_b32_e32 v75, v3
	v_lshlrev_b32_e32 v80, 2, v12
	v_mov_b32_e32 v81, v3
	v_lshlrev_b32_e32 v82, 2, v14
	v_mov_b32_e32 v83, v3
	v_lshl_add_u64 v[64:65], v[92:93], 0, v[58:59]
	v_lshl_add_u64 v[68:69], v[92:93], 0, v[60:61]
	v_lshl_add_u64 v[72:73], v[92:93], 0, v[62:63]
	v_lshl_add_u64 v[76:77], v[92:93], 0, v[74:75]
	v_lshl_add_u64 v[80:81], v[92:93], 0, v[80:81]
	v_lshl_add_u64 v[84:85], v[92:93], 0, v[82:83]
	global_load_dwordx4 v[64:67], v[64:65], off nt
	s_nop 0
	global_load_dwordx4 v[68:71], v[68:69], off nt
	s_nop 0
	global_load_dwordx4 v[72:75], v[72:73], off nt
	s_nop 0
	global_load_dwordx4 v[76:79], v[76:77], off nt
	s_nop 0
	global_load_dwordx4 v[80:83], v[80:81], off nt
	s_nop 0
	global_load_dwordx4 v[84:87], v[84:85], off nt
	v_lshlrev_b32_e32 v88, 2, v16
	v_mov_b32_e32 v89, v3
	v_lshl_add_u64 v[88:89], v[92:93], 0, v[88:89]
	global_load_dwordx4 v[88:91], v[88:89], off nt
	v_lshlrev_b32_e32 v94, 2, v18
	v_mov_b32_e32 v95, v3
	v_lshl_add_u64 v[92:93], v[92:93], 0, v[94:95]
	global_load_dwordx4 v[92:95], v[92:93], off nt
	v_add_u32_e32 v19, v13, v15
	v_add_u32_e32 v27, 0x420, v19
	v_add_u32_e32 v29, 0x428, v19
	v_add_u32_e32 v31, 0x840, v19
	v_add_u32_e32 v33, 0x848, v19
	v_add_u32_e32 v35, 0xc60, v19
	v_add_u32_e32 v37, 0xc68, v19
	v_add_u32_e32 v39, 0x1080, v19
	v_add_u32_e32 v41, 0x1088, v19
	v_add_u32_e32 v43, 0x14a0, v19
	v_add_u32_e32 v45, 0x14a8, v19
	v_add_u32_e32 v47, 0x18c0, v19
	v_add_u32_e32 v49, 0x18c8, v19
	v_add_u32_e32 v51, 0x1ce0, v19
	v_add_u32_e32 v53, 0x1ce8, v19
	s_lshl_b32 s4, s59, 10
	s_add_u32 s4, s21, s4
	s_addc_u32 s19, s57, 0
	s_lshl_b32 s18, s58, 1
	s_add_u32 s18, s4, s18
	v_lshlrev_b32_e32 v96, 1, v20
	v_mov_b32_e32 v97, v3
	s_addc_u32 s19, s19, 0
	v_lshl_add_u64 v[96:97], s[18:19], 0, v[96:97]
	v_lshl_add_u64 v[96:97], v[96:97], 0, s[14:15]
	s_waitcnt vmcnt(7)
	ds_write2_b32 v19, v64, v65 offset1:1
	ds_write2_b32 v19, v66, v67 offset0:2 offset1:3
	s_waitcnt vmcnt(6)
	ds_write2_b32 v27, v68, v69 offset1:1
	ds_write2_b32 v29, v70, v71 offset1:1
	s_waitcnt vmcnt(5)
	ds_write2_b32 v31, v72, v73 offset1:1
	ds_write2_b32 v33, v74, v75 offset1:1
	s_waitcnt vmcnt(4)
	ds_write2_b32 v35, v76, v77 offset1:1
	ds_write2_b32 v37, v78, v79 offset1:1
	s_waitcnt vmcnt(3)
	ds_write2_b32 v39, v80, v81 offset1:1
	ds_write2_b32 v41, v82, v83 offset1:1
	s_waitcnt vmcnt(2)
	ds_write2_b32 v43, v84, v85 offset1:1
	ds_write2_b32 v45, v86, v87 offset1:1
	s_waitcnt vmcnt(1)
	ds_write2_b32 v47, v88, v89 offset1:1
	ds_write2_b32 v49, v90, v91 offset1:1
	s_waitcnt vmcnt(0)
	ds_write2_b32 v51, v92, v93 offset1:1
	ds_write2_b32 v53, v94, v95 offset1:1
	s_waitcnt lgkmcnt(0)
	ds_read2_b32 v[68:69], v17 offset0:33 offset1:41
	ds_read2_b32 v[70:71], v17 offset1:8
	ds_read2_b32 v[72:73], v17 offset0:66 offset1:74
	ds_read2_b32 v[74:75], v17 offset0:99 offset1:107
	ds_read2_b32 v[76:77], v17 offset0:132 offset1:140
	ds_read2_b32 v[78:79], v17 offset0:165 offset1:173
	s_waitcnt lgkmcnt(4)
	v_bfe_u32 v19, v70, 16, 1
	v_bfe_u32 v27, v68, 16, 1
	v_add3_u32 v19, v70, v19, s46
	ds_read2_b32 v[80:81], v17 offset0:198 offset1:206
	v_add3_u32 v27, v68, v27, s46
	v_lshrrev_b32_e32 v19, 16, v19
	ds_read2_b32 v[82:83], v17 offset0:231 offset1:239
	v_and_or_b32 v64, v27, s47, v19
	s_waitcnt lgkmcnt(3)
; #define LAS __attribute__((address_space(3)))
; __device__ __forceinline__ unsigned f2bf(float f) { unsigned u = __builtin_bit_cast(unsigned, f); return (u + 0x7fffu + ((u >> 16) & 1u)) >> 16; }
; __device__ __forceinline__ unsigned pk2(float lo, float hi) { return f2bf(lo) | (f2bf(hi) << 16); }
; __device__ __forceinline__ void tr_block(const float* src  , int ldw, bf16* dst  , int K, LAS float* scr, int lane) {
;     ...
;     const int c = lane & 7;
; #pragma unroll
;     for (int j = 0; j < 4; ++j) { const int n = (lane >> 3) + 8 * j; const LAS float* s = scr + (8 * c) * 33 + n;
;         v4u o; o.x = pk2(s[0 * 33], s[1 * 33]); o.y = pk2(s[2 * 33], s[3 * 33]); o.z = pk2(s[4 * 33], s[5 * 33]); o.w = pk2(s[6 * 33], s[7 * 33]);
;         *(v4u*)(dst + (size_t)n * K + 8 * c) = o; }
;     asm volatile("s_waitcnt lgkmcnt(0)" ::: "memory");
	v_bfe_u32 v19, v76, 16, 1
	v_add3_u32 v19, v76, v19, s46
	s_waitcnt lgkmcnt(2)
	v_bfe_u32 v27, v78, 16, 1
	v_lshrrev_b32_e32 v19, 16, v19
	v_add3_u32 v27, v78, v27, s46
	v_and_or_b32 v66, v27, s47, v19
	s_waitcnt lgkmcnt(1)
	v_bfe_u32 v19, v80, 16, 1
	v_add3_u32 v19, v80, v19, s46
	s_waitcnt lgkmcnt(0)
	v_bfe_u32 v27, v82, 16, 1
	v_bfe_u32 v29, v72, 16, 1
	v_lshrrev_b32_e32 v19, 16, v19
	v_add3_u32 v27, v82, v27, s46
	v_bfe_u32 v31, v74, 16, 1
	v_add3_u32 v29, v72, v29, s46
	v_and_or_b32 v67, v27, s47, v19
	v_bfe_u32 v19, v71, 16, 1
	v_add3_u32 v31, v74, v31, s46
	v_lshrrev_b32_e32 v29, 16, v29
	v_lshlrev_b32_e32 v84, 1, v26
	v_mov_b32_e32 v85, v3
	v_add3_u32 v19, v71, v19, s46
	v_bfe_u32 v27, v69, 16, 1
	v_and_or_b32 v65, v31, s47, v29
	v_lshl_add_u64 v[84:85], v[96:97], 0, v[84:85]
	v_lshrrev_b32_e32 v19, 16, v19
	v_add3_u32 v27, v69, v27, s46
	global_store_dwordx4 v[84:85], v[64:67], off
	v_lshlrev_b32_e32 v68, 1, v28
	v_mov_b32_e32 v69, v3
	v_and_or_b32 v64, v27, s47, v19
	v_bfe_u32 v19, v73, 16, 1
	v_add3_u32 v19, v73, v19, s46
	v_bfe_u32 v27, v75, 16, 1
	v_lshrrev_b32_e32 v19, 16, v19
	v_add3_u32 v27, v75, v27, s46
	v_and_or_b32 v65, v27, s47, v19
	v_bfe_u32 v19, v77, 16, 1
	v_add3_u32 v19, v77, v19, s46
	v_bfe_u32 v27, v79, 16, 1
	v_lshrrev_b32_e32 v19, 16, v19
	v_add3_u32 v27, v79, v27, s46
	v_and_or_b32 v66, v27, s47, v19
	v_bfe_u32 v19, v81, 16, 1
	v_add3_u32 v19, v81, v19, s46
	v_bfe_u32 v27, v83, 16, 1
	v_lshrrev_b32_e32 v19, 16, v19
	v_add3_u32 v27, v83, v27, s46
	v_and_or_b32 v67, v27, s47, v19
	ds_read2_b32 v[70:71], v17 offset0:16 offset1:24
	v_lshl_add_u64 v[68:69], v[96:97], 0, v[68:69]
	global_store_dwordx4 v[68:69], v[64:67], off
	ds_read2_b32 v[68:69], v17 offset0:49 offset1:57
	ds_read2_b32 v[72:73], v17 offset0:82 offset1:90
	ds_read2_b32 v[74:75], v17 offset0:115 offset1:123
	s_waitcnt lgkmcnt(3)
	v_bfe_u32 v19, v70, 16, 1
	v_add3_u32 v19, v70, v19, s46
	s_waitcnt lgkmcnt(2)
	v_bfe_u32 v27, v68, 16, 1
	ds_read2_b32 v[76:77], v17 offset0:148 offset1:156
	v_lshrrev_b32_e32 v19, 16, v19
	v_add3_u32 v27, v68, v27, s46
	ds_read2_b32 v[78:79], v17 offset0:181 offset1:189
	v_and_or_b32 v64, v27, s47, v19
	s_waitcnt lgkmcnt(3)
	v_bfe_u32 v19, v72, 16, 1
	v_add3_u32 v19, v72, v19, s46
	s_waitcnt lgkmcnt(2)
	v_bfe_u32 v27, v74, 16, 1
	ds_read2_b32 v[80:81], v17 offset0:214 offset1:222
	v_lshrrev_b32_e32 v19, 16, v19
	v_add3_u32 v27, v74, v27, s46
	ds_read2_b32 v[82:83], v17 offset0:247 offset1:255
	v_and_or_b32 v65, v27, s47, v19
	s_waitcnt lgkmcnt(3)
	v_bfe_u32 v19, v76, 16, 1
	v_add3_u32 v19, v76, v19, s46
	s_waitcnt lgkmcnt(2)
	v_bfe_u32 v27, v78, 16, 1
	v_lshrrev_b32_e32 v19, 16, v19
	v_add3_u32 v27, v78, v27, s46
	v_and_or_b32 v66, v27, s47, v19
	s_waitcnt lgkmcnt(1)
	v_bfe_u32 v19, v80, 16, 1
	v_add3_u32 v19, v80, v19, s46
	s_waitcnt lgkmcnt(0)
	v_bfe_u32 v27, v82, 16, 1
	v_lshrrev_b32_e32 v19, 16, v19
	v_add3_u32 v27, v82, v27, s46
	v_and_or_b32 v67, v27, s47, v19
	v_bfe_u32 v19, v71, 16, 1
	v_lshlrev_b32_e32 v84, 1, v30
	v_mov_b32_e32 v85, v3
	v_add3_u32 v19, v71, v19, s46
	v_bfe_u32 v27, v69, 16, 1
	v_lshl_add_u64 v[84:85], v[96:97], 0, v[84:85]
	v_lshrrev_b32_e32 v19, 16, v19
	v_add3_u32 v27, v69, v27, s46
	global_store_dwordx4 v[84:85], v[64:67], off
	v_lshlrev_b32_e32 v68, 1, v32
	v_mov_b32_e32 v69, v3
	v_and_or_b32 v64, v27, s47, v19
	v_bfe_u32 v19, v73, 16, 1
	v_add3_u32 v19, v73, v19, s46
	v_bfe_u32 v27, v75, 16, 1
	v_lshrrev_b32_e32 v19, 16, v19
	v_add3_u32 v27, v75, v27, s46
	v_and_or_b32 v65, v27, s47, v19
	v_bfe_u32 v19, v77, 16, 1
	v_add3_u32 v19, v77, v19, s46
	v_bfe_u32 v27, v79, 16, 1
	v_lshrrev_b32_e32 v19, 16, v19
	v_add3_u32 v27, v79, v27, s46
	v_and_or_b32 v66, v27, s47, v19
	v_bfe_u32 v19, v81, 16, 1
	v_add3_u32 v19, v81, v19, s46
	v_bfe_u32 v27, v83, 16, 1
	v_lshrrev_b32_e32 v19, 16, v19
	v_add3_u32 v27, v83, v27, s46
	v_and_or_b32 v67, v27, s47, v19
	v_lshl_add_u64 v[68:69], v[96:97], 0, v[68:69]
	global_store_dwordx4 v[68:69], v[64:67], off
	s_waitcnt lgkmcnt(0)

; #define LAS __attribute__((address_space(3)))
; __device__ __forceinline__ unsigned pk2(float lo, float hi) { return f2bf(lo) | (f2bf(hi) << 16); }
; __device__ __forceinline__ void tr_block(const float* src  , int ldw, bf16* dst  , int K, LAS float* scr, int lane) {
;     const int kr = lane >> 3, c4 = lane & 7;
;     f32x4 v[8];
; #pragma unroll
;     for (int i = 0; i < 8; ++i) v[i] = *(const f32x4*)(src + (size_t)(8 * i + kr) * ldw + 4 * c4);
; #pragma unroll
;     for (int i = 0; i < 8; ++i) { LAS float* d = scr + (8 * i + kr) * 33 + 4 * c4; d[0] = v[i].x; d[1] = v[i].y; d[2] = v[i].z; d[3] = v[i].w; }
;     asm volatile("s_waitcnt lgkmcnt(0)" ::: "memory");
;     const int c = lane & 7;
; #pragma unroll
;     for (int j = 0; j < 4; ++j) { const int n = (lane >> 3) + 8 * j; const LAS float* s = scr + (8 * c) * 33 + n;
;         v4u o; o.x = pk2(s[0 * 33], s[1 * 33]); o.y = pk2(s[2 * 33], s[3 * 33]); o.z = pk2(s[4 * 33], s[5 * 33]); o.w = pk2(s[6 * 33], s[7 * 33]);
;         *(v4u*)(dst + (size_t)n * K + 8 * c) = o; }
;     asm volatile("s_waitcnt lgkmcnt(0)" ::: "memory");
; }
.LBB0_36:
	s_andn2_b64 vcc, exec, s[20:21]
	s_cbranch_vccnz .LBB0_38
	s_add_i32 s4, s54, 0xfd00
	s_bfe_u32 s18, s4, 0xc0004
	s_mulk_i32 s18, 0x2493
	s_lshr_b32 s20, s18, 16
	s_mul_i32 s18, s20, 0x70
	s_sub_i32 s4, s4, s18
	s_lshl_b32 s18, s4, 5
	s_add_i32 s21, s18, 0x600
	s_mul_i32 s18, s20, 0x140800
	s_add_u32 s18, s55, s18
	s_addc_u32 s19, s56, 0
	s_lshl_b32 s4, s4, 7
	s_and_b32 s4, s4, 0x3ff80
	s_add_u32 s18, s18, s4
	s_addc_u32 s19, s19, 0
	v_lshl_add_u64 v[64:65], s[18:19], 0, v[2:3]
	v_lshl_add_u64 v[80:81], v[64:65], 0, s[16:17]
	v_lshlrev_b32_e32 v64, 2, v34
	v_mov_b32_e32 v65, v3
	v_lshl_add_u64 v[92:93], v[80:81], 0, v[64:65]
	v_add_co_u32_e32 v68, vcc, s48, v92
	v_lshlrev_b32_e32 v72, 2, v36
	s_nop 0
	v_addc_co_u32_e32 v69, vcc, 0, v93, vcc
	v_add_co_u32_e32 v84, vcc, s49, v92
	v_mov_b32_e32 v73, v3
	s_nop 0
	v_addc_co_u32_e32 v85, vcc, 0, v93, vcc
	v_lshlrev_b32_e32 v74, 2, v38
	v_mov_b32_e32 v75, v3
	v_lshlrev_b32_e32 v82, 2, v40
	v_mov_b32_e32 v83, v3
	v_add_co_u32_e32 v88, vcc, s50, v92
	v_lshl_add_u64 v[72:73], v[80:81], 0, v[72:73]
	v_lshl_add_u64 v[76:77], v[80:81], 0, v[74:75]
	v_lshl_add_u64 v[80:81], v[80:81], 0, v[82:83]
	v_addc_co_u32_e32 v89, vcc, 0, v93, vcc
	global_load_dwordx4 v[64:67], v[92:93], off nt
	s_nop 0
	global_load_dwordx4 v[68:71], v[68:69], off offset:256
	s_nop 0
	global_load_dwordx4 v[72:75], v[72:73], off nt
	s_nop 0
	global_load_dwordx4 v[76:79], v[76:77], off nt
	v_add_co_u32_e32 v92, vcc, s51, v92
	global_load_dwordx4 v[80:83], v[80:81], off nt
	s_nop 0
	global_load_dwordx4 v[84:87], v[84:85], off offset:512
	s_nop 0
	global_load_dwordx4 v[88:91], v[88:89], off offset:768
	v_addc_co_u32_e32 v93, vcc, 0, v93, vcc
	global_load_dwordx4 v[92:95], v[92:93], off offset:1024
	v_add_u32_e32 v19, v13, v15
	v_add_u32_e32 v27, 0x420, v19
	v_add_u32_e32 v29, 0x428, v19
	v_add_u32_e32 v31, 0x840, v19
	v_add_u32_e32 v33, 0x848, v19
	v_add_u32_e32 v35, 0xc60, v19
	v_add_u32_e32 v37, 0xc68, v19
	v_add_u32_e32 v39, 0x1080, v19
	v_add_u32_e32 v41, 0x1088, v19
	v_add_u32_e32 v43, 0x14a0, v19
	v_add_u32_e32 v45, 0x14a8, v19
	v_add_u32_e32 v47, 0x18c0, v19
	v_add_u32_e32 v49, 0x18c8, v19
	v_add_u32_e32 v51, 0x1ce0, v19
	v_add_u32_e32 v53, 0x1ce8, v19
	s_and_b32 s4, s21, 0xffe0
	s_lshl_b32 s4, s4, 11
	s_add_u32 s4, s52, s4
	s_addc_u32 s19, s53, 0
	s_lshl_b32 s18, s20, 7
	s_add_u32 s18, s4, s18
	v_lshlrev_b32_e32 v96, 1, v20
	v_mov_b32_e32 v97, v3
	s_addc_u32 s19, s19, 0
	s_waitcnt vmcnt(7)
	ds_write2_b32 v19, v64, v65 offset1:1
	ds_write2_b32 v19, v66, v67 offset0:2 offset1:3
	s_waitcnt vmcnt(5)
	ds_write2_b32 v43, v72, v73 offset1:1
	ds_write2_b32 v45, v74, v75 offset1:1
	s_waitcnt vmcnt(4)
	ds_write2_b32 v47, v76, v77 offset1:1
	ds_write2_b32 v49, v78, v79 offset1:1
	s_waitcnt vmcnt(3)
	ds_write2_b32 v51, v80, v81 offset1:1
	ds_write2_b32 v53, v82, v83 offset1:1
	ds_write2_b32 v27, v68, v69 offset1:1
	ds_write2_b32 v29, v70, v71 offset1:1
	s_waitcnt vmcnt(2)
	ds_write2_b32 v31, v84, v85 offset1:1
	ds_write2_b32 v33, v86, v87 offset1:1
	s_waitcnt vmcnt(1)
	ds_write2_b32 v35, v88, v89 offset1:1
	ds_write2_b32 v37, v90, v91 offset1:1
	s_waitcnt vmcnt(0)
	ds_write2_b32 v39, v92, v93 offset1:1
	ds_write2_b32 v41, v94, v95 offset1:1
	s_waitcnt lgkmcnt(0)
	ds_read2_b32 v[68:69], v17 offset1:8
	ds_read2_b32 v[70:71], v17 offset0:33 offset1:41
	ds_read2_b32 v[72:73], v17 offset0:66 offset1:74
	ds_read2_b32 v[76:77], v17 offset0:99 offset1:107
	ds_read2_b32 v[78:79], v17 offset0:132 offset1:140
	s_waitcnt lgkmcnt(4)
	v_bfe_u32 v19, v68, 16, 1
	s_waitcnt lgkmcnt(3)
	v_bfe_u32 v27, v70, 16, 1
	v_add3_u32 v19, v68, v19, s46
	ds_read2_b32 v[80:81], v17 offset0:165 offset1:173
	s_waitcnt lgkmcnt(3)
	v_bfe_u32 v29, v72, 16, 1
	v_add3_u32 v27, v70, v27, s46
	v_lshrrev_b32_e32 v19, 16, v19
	v_add3_u32 v29, v72, v29, s46
	v_and_or_b32 v64, v27, s47, v19
	s_waitcnt lgkmcnt(2)
; #define LAS __attribute__((address_space(3)))
; __device__ __forceinline__ unsigned f2bf(float f) { unsigned u = __builtin_bit_cast(unsigned, f); return (u + 0x7fffu + ((u >> 16) & 1u)) >> 16; }
; __device__ __forceinline__ unsigned pk2(float lo, float hi) { return f2bf(lo) | (f2bf(hi) << 16); }
; __device__ __forceinline__ void tr_block(const float* src  , int ldw, bf16* dst  , int K, LAS float* scr, int lane) {
;     ...
;     const int c = lane & 7;
; #pragma unroll
;     for (int j = 0; j < 4; ++j) { const int n = (lane >> 3) + 8 * j; const LAS float* s = scr + (8 * c) * 33 + n;
;         v4u o; o.x = pk2(s[0 * 33], s[1 * 33]); o.y = pk2(s[2 * 33], s[3 * 33]); o.z = pk2(s[4 * 33], s[5 * 33]); o.w = pk2(s[6 * 33], s[7 * 33]);
;         *(v4u*)(dst + (size_t)n * K + 8 * c) = o; }
;     asm volatile("s_waitcnt lgkmcnt(0)" ::: "memory");
	v_bfe_u32 v19, v76, 16, 1
	ds_read2_b32 v[82:83], v17 offset0:198 offset1:206
	v_lshrrev_b32_e32 v29, 16, v29
	v_add3_u32 v19, v76, v19, s46
	ds_read2_b32 v[84:85], v17 offset0:231 offset1:239
	v_and_or_b32 v65, v19, s47, v29
	s_waitcnt lgkmcnt(3)
	v_bfe_u32 v19, v78, 16, 1
	v_add3_u32 v19, v78, v19, s46
	s_waitcnt lgkmcnt(2)
	v_bfe_u32 v27, v80, 16, 1
	v_lshrrev_b32_e32 v19, 16, v19
	v_add3_u32 v27, v80, v27, s46
	v_and_or_b32 v66, v27, s47, v19
	s_waitcnt lgkmcnt(1)
	v_bfe_u32 v19, v82, 16, 1
	v_add3_u32 v19, v82, v19, s46
	s_waitcnt lgkmcnt(0)
	v_bfe_u32 v27, v84, 16, 1
	v_lshrrev_b32_e32 v19, 16, v19
	v_add3_u32 v27, v84, v27, s46
	v_and_or_b32 v67, v27, s47, v19
	v_bfe_u32 v19, v69, 16, 1
	v_lshl_add_u64 v[74:75], s[18:19], 0, v[96:97]
	v_lshlrev_b32_e32 v86, 1, v4
	v_mov_b32_e32 v87, v3
	v_add3_u32 v19, v69, v19, s46
	v_bfe_u32 v27, v71, 16, 1
	v_lshl_add_u64 v[86:87], v[74:75], 0, v[86:87]
	v_lshrrev_b32_e32 v19, 16, v19
	v_add3_u32 v27, v71, v27, s46
	global_store_dwordx4 v[86:87], v[64:67], off
	v_lshlrev_b32_e32 v68, 1, v6
	v_mov_b32_e32 v69, v3
	v_and_or_b32 v64, v27, s47, v19
	v_bfe_u32 v19, v73, 16, 1
	v_add3_u32 v19, v73, v19, s46
	v_bfe_u32 v27, v77, 16, 1
	v_lshrrev_b32_e32 v19, 16, v19
	v_add3_u32 v27, v77, v27, s46
	v_and_or_b32 v65, v27, s47, v19
	v_bfe_u32 v19, v79, 16, 1
	v_add3_u32 v19, v79, v19, s46
	v_bfe_u32 v27, v81, 16, 1
	v_lshrrev_b32_e32 v19, 16, v19
	v_add3_u32 v27, v81, v27, s46
	v_and_or_b32 v66, v27, s47, v19
	v_bfe_u32 v19, v83, 16, 1
	v_add3_u32 v19, v83, v19, s46
	v_bfe_u32 v27, v85, 16, 1
	v_lshrrev_b32_e32 v19, 16, v19
	v_add3_u32 v27, v85, v27, s46
	v_and_or_b32 v67, v27, s47, v19
	ds_read2_b32 v[70:71], v17 offset0:16 offset1:24
	v_lshl_add_u64 v[68:69], v[74:75], 0, v[68:69]
	global_store_dwordx4 v[68:69], v[64:67], off
	ds_read2_b32 v[68:69], v17 offset0:49 offset1:57
	ds_read2_b32 v[72:73], v17 offset0:82 offset1:90
	ds_read2_b32 v[76:77], v17 offset0:115 offset1:123
	s_waitcnt lgkmcnt(3)
	v_bfe_u32 v19, v70, 16, 1
	v_add3_u32 v19, v70, v19, s46
	s_waitcnt lgkmcnt(2)
	v_bfe_u32 v27, v68, 16, 1
	ds_read2_b32 v[78:79], v17 offset0:148 offset1:156
	v_lshrrev_b32_e32 v19, 16, v19
	v_add3_u32 v27, v68, v27, s46
	ds_read2_b32 v[80:81], v17 offset0:181 offset1:189
	v_and_or_b32 v64, v27, s47, v19
	s_waitcnt lgkmcnt(3)
	v_bfe_u32 v19, v72, 16, 1
	v_add3_u32 v19, v72, v19, s46
	s_waitcnt lgkmcnt(2)
	v_bfe_u32 v27, v76, 16, 1
	ds_read2_b32 v[82:83], v17 offset0:214 offset1:222
	v_lshrrev_b32_e32 v19, 16, v19
	v_add3_u32 v27, v76, v27, s46
	ds_read2_b32 v[84:85], v17 offset0:247 offset1:255
	v_and_or_b32 v65, v27, s47, v19
	s_waitcnt lgkmcnt(3)
	v_bfe_u32 v19, v78, 16, 1
	v_add3_u32 v19, v78, v19, s46
	s_waitcnt lgkmcnt(2)
	v_bfe_u32 v27, v80, 16, 1
	v_lshrrev_b32_e32 v19, 16, v19
	v_add3_u32 v27, v80, v27, s46
	v_and_or_b32 v66, v27, s47, v19
	s_waitcnt lgkmcnt(1)
	v_bfe_u32 v19, v82, 16, 1
	v_add3_u32 v19, v82, v19, s46
	s_waitcnt lgkmcnt(0)
	v_bfe_u32 v27, v84, 16, 1
	v_lshrrev_b32_e32 v19, 16, v19
	v_add3_u32 v27, v84, v27, s46
	v_and_or_b32 v67, v27, s47, v19
	v_bfe_u32 v19, v71, 16, 1
	v_lshlrev_b32_e32 v86, 1, v8
	v_mov_b32_e32 v87, v3
	v_add3_u32 v19, v71, v19, s46
	v_bfe_u32 v27, v69, 16, 1
	v_lshl_add_u64 v[86:87], v[74:75], 0, v[86:87]
	v_lshrrev_b32_e32 v19, 16, v19
	v_add3_u32 v27, v69, v27, s46
	global_store_dwordx4 v[86:87], v[64:67], off
	v_lshlrev_b32_e32 v68, 1, v10
	v_mov_b32_e32 v69, v3
	v_and_or_b32 v64, v27, s47, v19
	v_bfe_u32 v19, v73, 16, 1
	v_add3_u32 v19, v73, v19, s46
	v_bfe_u32 v27, v77, 16, 1
	v_lshrrev_b32_e32 v19, 16, v19
	v_add3_u32 v27, v77, v27, s46
	v_and_or_b32 v65, v27, s47, v19
	v_bfe_u32 v19, v79, 16, 1
	v_add3_u32 v19, v79, v19, s46
	v_bfe_u32 v27, v81, 16, 1
	v_lshrrev_b32_e32 v19, 16, v19
	v_add3_u32 v27, v81, v27, s46
	v_and_or_b32 v66, v27, s47, v19
	v_bfe_u32 v19, v83, 16, 1
	v_add3_u32 v19, v83, v19, s46
	v_bfe_u32 v27, v85, 16, 1
	v_lshrrev_b32_e32 v19, 16, v19
	v_add3_u32 v27, v85, v27, s46
	v_and_or_b32 v67, v27, s47, v19
	v_lshl_add_u64 v[68:69], v[74:75], 0, v[68:69]
	global_store_dwordx4 v[68:69], v[64:67], off
	s_waitcnt lgkmcnt(0)

; #define LAS __attribute__((address_space(3)))
; __device__ __forceinline__ unsigned pk2(float lo, float hi) { return f2bf(lo) | (f2bf(hi) << 16); }
; __device__ __forceinline__ void tr_block(const float* src  , int ldw, bf16* dst  , int K, LAS float* scr, int lane) {
;     const int kr = lane >> 3, c4 = lane & 7;
;     f32x4 v[8];
; #pragma unroll
;     for (int i = 0; i < 8; ++i) v[i] = *(const f32x4*)(src + (size_t)(8 * i + kr) * ldw + 4 * c4);
; #pragma unroll
;     for (int i = 0; i < 8; ++i) { LAS float* d = scr + (8 * i + kr) * 33 + 4 * c4; d[0] = v[i].x; d[1] = v[i].y; d[2] = v[i].z; d[3] = v[i].w; }
;     asm volatile("s_waitcnt lgkmcnt(0)" ::: "memory");
;     const int c = lane & 7;
; #pragma unroll
;     for (int j = 0; j < 4; ++j) { const int n = (lane >> 3) + 8 * j; const LAS float* s = scr + (8 * c) * 33 + n;
;         v4u o; o.x = pk2(s[0 * 33], s[1 * 33]); o.y = pk2(s[2 * 33], s[3 * 33]); o.z = pk2(s[4 * 33], s[5 * 33]); o.w = pk2(s[6 * 33], s[7 * 33]);
;         *(v4u*)(dst + (size_t)n * K + 8 * c) = o; }
;     asm volatile("s_waitcnt lgkmcnt(0)" ::: "memory");
; }
.LBB0_39:
	s_andn2_b64 vcc, exec, s[20:21]
	s_cbranch_vccnz .LBB0_9
	s_mul_hi_i32 s4, s54, 0x2aaaaaab
	s_lshr_b32 s18, s4, 31
	s_ashr_i32 s4, s4, 3
	s_add_i32 s4, s4, s18
	s_mul_i32 s18, s4, 48
	s_sub_i32 s19, s54, s18
	s_lshl_b32 s18, s4, 6
	s_lshl_b32 s20, s19, 5
	s_ashr_i32 s19, s18, 31
	s_mul_i32 s4, s4, 0x140800
	s_mul_hi_i32 s21, s18, 0x5020
	s_add_u32 s4, s55, s4
	s_addc_u32 s56, s56, s21
	s_ashr_i32 s21, s20, 31
	s_lshl_b64 s[54:55], s[20:21], 2
	s_add_u32 s54, s4, s54
	s_addc_u32 s55, s56, s55
	v_lshl_add_u64 v[92:93], s[54:55], 0, v[2:3]
	v_lshlrev_b32_e32 v64, 2, v34
	v_mov_b32_e32 v65, v3
	v_lshl_add_u64 v[88:89], v[92:93], 0, v[64:65]
	v_add_co_u32_e32 v68, vcc, s48, v88
	v_lshlrev_b32_e32 v72, 2, v38
	s_nop 0
	v_addc_co_u32_e32 v69, vcc, 0, v89, vcc
	v_add_co_u32_e32 v80, vcc, s49, v88
	v_mov_b32_e32 v73, v3
	s_nop 0
	v_addc_co_u32_e32 v81, vcc, 0, v89, vcc
	v_add_co_u32_e32 v84, vcc, s50, v88
	v_lshlrev_b32_e32 v74, 2, v40
	v_mov_b32_e32 v75, v3
	v_addc_co_u32_e32 v85, vcc, 0, v89, vcc
	v_lshl_add_u64 v[72:73], v[92:93], 0, v[72:73]
	v_lshl_add_u64 v[76:77], v[92:93], 0, v[74:75]
	global_load_dwordx4 v[64:67], v[88:89], off nt
	s_nop 0
	global_load_dwordx4 v[68:71], v[68:69], off offset:256
	s_nop 0
	global_load_dwordx4 v[72:75], v[72:73], off nt
	s_nop 0
	global_load_dwordx4 v[76:79], v[76:77], off nt
	s_nop 0
	global_load_dwordx4 v[80:83], v[80:81], off offset:512
	s_nop 0
	global_load_dwordx4 v[84:87], v[84:85], off offset:768
	v_add_co_u32_e32 v88, vcc, s51, v88
	v_lshlrev_b32_e32 v94, 2, v36
	s_nop 0
	v_addc_co_u32_e32 v89, vcc, 0, v89, vcc
	global_load_dwordx4 v[88:91], v[88:89], off offset:1024
	v_mov_b32_e32 v95, v3
	v_lshl_add_u64 v[92:93], v[92:93], 0, v[94:95]
	global_load_dwordx4 v[92:95], v[92:93], off nt
	v_add_u32_e32 v19, v13, v15
	v_add_u32_e32 v27, 0x420, v19
	v_add_u32_e32 v29, 0x428, v19
	v_add_u32_e32 v31, 0x840, v19
	v_add_u32_e32 v33, 0x848, v19
	v_add_u32_e32 v35, 0xc60, v19
	v_add_u32_e32 v37, 0xc68, v19
	v_add_u32_e32 v39, 0x1080, v19
	v_add_u32_e32 v41, 0x1088, v19
	v_add_u32_e32 v43, 0x14a0, v19
	v_add_u32_e32 v45, 0x14a8, v19
	v_add_u32_e32 v47, 0x18c0, v19
	v_add_u32_e32 v49, 0x18c8, v19
	v_add_u32_e32 v51, 0x1ce0, v19
	v_add_u32_e32 v53, 0x1ce8, v19
	s_lshl_b64 s[20:21], s[20:21], 11
	s_add_u32 s4, s52, s20
	s_addc_u32 s20, s53, s21
	s_lshl_b64 s[18:19], s[18:19], 1
	s_add_u32 s18, s4, s18
	v_lshlrev_b32_e32 v96, 1, v20
	v_mov_b32_e32 v97, v3
	s_addc_u32 s19, s20, s19
	s_waitcnt vmcnt(7)
	ds_write2_b32 v19, v64, v65 offset1:1
	ds_write2_b32 v19, v66, v67 offset0:2 offset1:3
	s_waitcnt vmcnt(5)
	ds_write2_b32 v47, v72, v73 offset1:1
	ds_write2_b32 v49, v74, v75 offset1:1
	s_waitcnt vmcnt(4)
	ds_write2_b32 v51, v76, v77 offset1:1
	ds_write2_b32 v53, v78, v79 offset1:1
	ds_write2_b32 v27, v68, v69 offset1:1
	ds_write2_b32 v29, v70, v71 offset1:1
	s_waitcnt vmcnt(3)
	ds_write2_b32 v31, v80, v81 offset1:1
	ds_write2_b32 v33, v82, v83 offset1:1
	s_waitcnt vmcnt(2)
	ds_write2_b32 v35, v84, v85 offset1:1
	ds_write2_b32 v37, v86, v87 offset1:1
	s_waitcnt vmcnt(1)
	ds_write2_b32 v39, v88, v89 offset1:1
	ds_write2_b32 v41, v90, v91 offset1:1
	s_waitcnt vmcnt(0)
	ds_write2_b32 v43, v92, v93 offset1:1
	ds_write2_b32 v45, v94, v95 offset1:1
	s_waitcnt lgkmcnt(0)
	ds_read2_b32 v[68:69], v17 offset1:8
	ds_read2_b32 v[70:71], v17 offset0:33 offset1:41
	ds_read2_b32 v[74:75], v17 offset0:66 offset1:74
	ds_read2_b32 v[76:77], v17 offset0:99 offset1:107
	ds_read2_b32 v[78:79], v17 offset0:132 offset1:140
	ds_read2_b32 v[80:81], v17 offset0:165 offset1:173
	s_waitcnt lgkmcnt(5)
	v_bfe_u32 v19, v68, 16, 1
	s_waitcnt lgkmcnt(4)
	v_bfe_u32 v27, v70, 16, 1
	v_add3_u32 v19, v68, v19, s46
	v_add3_u32 v27, v70, v27, s46
	v_lshrrev_b32_e32 v19, 16, v19
	v_and_or_b32 v64, v27, s47, v19
	s_waitcnt lgkmcnt(3)
	v_bfe_u32 v19, v74, 16, 1
	v_add3_u32 v19, v74, v19, s46
	s_waitcnt lgkmcnt(2)
; #define LAS __attribute__((address_space(3)))
; __device__ __forceinline__ unsigned f2bf(float f) { unsigned u = __builtin_bit_cast(unsigned, f); return (u + 0x7fffu + ((u >> 16) & 1u)) >> 16; }
; __device__ __forceinline__ unsigned pk2(float lo, float hi) { return f2bf(lo) | (f2bf(hi) << 16); }
; __device__ __forceinline__ void tr_block(const float* src  , int ldw, bf16* dst  , int K, LAS float* scr, int lane) {
;     ...
;     const int c = lane & 7;
; #pragma unroll
;     for (int j = 0; j < 4; ++j) { const int n = (lane >> 3) + 8 * j; const LAS float* s = scr + (8 * c) * 33 + n;
;         v4u o; o.x = pk2(s[0 * 33], s[1 * 33]); o.y = pk2(s[2 * 33], s[3 * 33]); o.z = pk2(s[4 * 33], s[5 * 33]); o.w = pk2(s[6 * 33], s[7 * 33]);
;         *(v4u*)(dst + (size_t)n * K + 8 * c) = o; }
;     asm volatile("s_waitcnt lgkmcnt(0)" ::: "memory");
	v_bfe_u32 v27, v76, 16, 1
	ds_read2_b32 v[82:83], v17 offset0:198 offset1:206
	v_lshrrev_b32_e32 v19, 16, v19
	v_add3_u32 v27, v76, v27, s46
	ds_read2_b32 v[84:85], v17 offset0:231 offset1:239
	v_and_or_b32 v65, v27, s47, v19
	s_waitcnt lgkmcnt(3)
	v_bfe_u32 v19, v78, 16, 1
	v_add3_u32 v19, v78, v19, s46
	s_waitcnt lgkmcnt(2)
	v_bfe_u32 v27, v80, 16, 1
	v_lshrrev_b32_e32 v19, 16, v19
	v_add3_u32 v27, v80, v27, s46
	v_and_or_b32 v66, v27, s47, v19
	s_waitcnt lgkmcnt(1)
	v_bfe_u32 v19, v82, 16, 1
	v_add3_u32 v19, v82, v19, s46
	s_waitcnt lgkmcnt(0)
	v_bfe_u32 v27, v84, 16, 1
	v_lshrrev_b32_e32 v19, 16, v19
	v_add3_u32 v27, v84, v27, s46
	v_and_or_b32 v67, v27, s47, v19
	v_bfe_u32 v19, v69, 16, 1
	v_lshl_add_u64 v[72:73], s[18:19], 0, v[96:97]
	v_lshlrev_b32_e32 v86, 1, v4
	v_mov_b32_e32 v87, v3
	v_add3_u32 v19, v69, v19, s46
	v_bfe_u32 v27, v71, 16, 1
	v_lshl_add_u64 v[86:87], v[72:73], 0, v[86:87]
	v_lshrrev_b32_e32 v19, 16, v19
	v_add3_u32 v27, v71, v27, s46
	global_store_dwordx4 v[86:87], v[64:67], off
	v_lshlrev_b32_e32 v68, 1, v6
	v_mov_b32_e32 v69, v3
	v_and_or_b32 v64, v27, s47, v19
	v_bfe_u32 v19, v75, 16, 1
	v_add3_u32 v19, v75, v19, s46
	v_bfe_u32 v27, v77, 16, 1
	v_lshrrev_b32_e32 v19, 16, v19
	v_add3_u32 v27, v77, v27, s46
	v_and_or_b32 v65, v27, s47, v19
	v_bfe_u32 v19, v79, 16, 1
	v_add3_u32 v19, v79, v19, s46
	v_bfe_u32 v27, v81, 16, 1
	v_lshrrev_b32_e32 v19, 16, v19
	v_add3_u32 v27, v81, v27, s46
	v_and_or_b32 v66, v27, s47, v19
	v_bfe_u32 v19, v83, 16, 1
	v_add3_u32 v19, v83, v19, s46
	v_bfe_u32 v27, v85, 16, 1
	v_lshrrev_b32_e32 v19, 16, v19
	v_add3_u32 v27, v85, v27, s46
	v_and_or_b32 v67, v27, s47, v19
	ds_read2_b32 v[70:71], v17 offset0:16 offset1:24
	v_lshl_add_u64 v[68:69], v[72:73], 0, v[68:69]
	global_store_dwordx4 v[68:69], v[64:67], off
	ds_read2_b32 v[68:69], v17 offset0:49 offset1:57
	ds_read2_b32 v[74:75], v17 offset0:82 offset1:90
	ds_read2_b32 v[76:77], v17 offset0:115 offset1:123
	s_waitcnt lgkmcnt(3)
	v_bfe_u32 v19, v70, 16, 1
	v_add3_u32 v19, v70, v19, s46
	s_waitcnt lgkmcnt(2)
	v_bfe_u32 v27, v68, 16, 1
	ds_read2_b32 v[78:79], v17 offset0:148 offset1:156
	v_lshrrev_b32_e32 v19, 16, v19
	v_add3_u32 v27, v68, v27, s46
	ds_read2_b32 v[80:81], v17 offset0:181 offset1:189
	v_and_or_b32 v64, v27, s47, v19
	s_waitcnt lgkmcnt(3)
	v_bfe_u32 v19, v74, 16, 1
	v_add3_u32 v19, v74, v19, s46
	s_waitcnt lgkmcnt(2)
	v_bfe_u32 v27, v76, 16, 1
	ds_read2_b32 v[82:83], v17 offset0:214 offset1:222
	v_lshrrev_b32_e32 v19, 16, v19
	v_add3_u32 v27, v76, v27, s46
	ds_read2_b32 v[84:85], v17 offset0:247 offset1:255
	v_and_or_b32 v65, v27, s47, v19
	s_waitcnt lgkmcnt(3)
	v_bfe_u32 v19, v78, 16, 1
	v_add3_u32 v19, v78, v19, s46
	s_waitcnt lgkmcnt(2)
	v_bfe_u32 v27, v80, 16, 1
	v_lshrrev_b32_e32 v19, 16, v19
	v_add3_u32 v27, v80, v27, s46
	v_and_or_b32 v66, v27, s47, v19
	s_waitcnt lgkmcnt(1)
	v_bfe_u32 v19, v82, 16, 1
	v_add3_u32 v19, v82, v19, s46
	s_waitcnt lgkmcnt(0)
	v_bfe_u32 v27, v84, 16, 1
	v_lshrrev_b32_e32 v19, 16, v19
	v_add3_u32 v27, v84, v27, s46
	v_and_or_b32 v67, v27, s47, v19
	v_bfe_u32 v19, v71, 16, 1
	v_lshlrev_b32_e32 v86, 1, v8
	v_mov_b32_e32 v87, v3
	v_add3_u32 v19, v71, v19, s46
	v_bfe_u32 v27, v69, 16, 1
	v_lshl_add_u64 v[86:87], v[72:73], 0, v[86:87]
	v_lshrrev_b32_e32 v19, 16, v19
	v_add3_u32 v27, v69, v27, s46
	global_store_dwordx4 v[86:87], v[64:67], off
	v_lshlrev_b32_e32 v68, 1, v10
	v_mov_b32_e32 v69, v3
	v_and_or_b32 v64, v27, s47, v19
	v_bfe_u32 v19, v75, 16, 1
	v_add3_u32 v19, v75, v19, s46
	v_bfe_u32 v27, v77, 16, 1
	v_lshrrev_b32_e32 v19, 16, v19
	v_add3_u32 v27, v77, v27, s46
	v_and_or_b32 v65, v27, s47, v19
	v_bfe_u32 v19, v79, 16, 1
	v_add3_u32 v19, v79, v19, s46
	v_bfe_u32 v27, v81, 16, 1
	v_lshrrev_b32_e32 v19, 16, v19
	v_add3_u32 v27, v81, v27, s46
	v_and_or_b32 v66, v27, s47, v19
	v_bfe_u32 v19, v83, 16, 1
	v_add3_u32 v19, v83, v19, s46
	v_bfe_u32 v27, v85, 16, 1
	v_lshrrev_b32_e32 v19, 16, v19
	v_add3_u32 v27, v85, v27, s46
	v_and_or_b32 v67, v27, s47, v19
	v_lshl_add_u64 v[68:69], v[72:73], 0, v[68:69]
	global_store_dwordx4 v[68:69], v[64:67], off
	s_waitcnt lgkmcnt(0)
	s_branch .LBB0_9
